# v10 + P0: nt (streaming) policy on the once-read f32 weight and x loads
# speedup vs baseline: 1.0451x; 1.0105x over previous
;     ...
;     for (int i = 0; i < 32; ++i) { const int k = k0 + 2 * i + (lane >> 5); wv[i] = W[(size_t)k * ldw + sc]; }
; #pragma unroll
;     for (int i = 0; i < 32; ++i) { const int kk = 2 * i + (lane >> 5), k = k0 + kk; float v = wv[i] * cs; if (gain && k < gain_lim) v *= gain[k]; scr[kk * 33 + (lane & 31)] = v; }
; __device__ __forceinline__ void p0_prologue(const Params& p, LAS unsigned char* lds, int G) {
;     ...
;         r -= I_IN;
;         { const int nb = r % 32, kb = r / 32, n0 = nb * 32;
;             p0_item(p.in[12], D, n0 + (lane & 31), p.in[9], 512, (bf16_t*)(p.ws + WS_WOUT), D, n0, kb * 64, scr, lane); }
.LBB0_26:
	v_cmp_lt_i32_e32 vcc, s38, v72
	s_and_saveexec_b64 s[0:1], vcc
	s_xor_b64 s[2:3], exec, s[0:1]
	s_cbranch_execz .LBB0_95
	s_movk_i32 s0, 0x20ff
	v_cmp_lt_u32_e32 vcc, s0, v72
	s_and_saveexec_b64 s[0:1], vcc
	s_xor_b64 s[28:29], exec, s[0:1]
	s_cbranch_execz .LBB0_92
	s_movk_i32 s0, 0x267f
	v_cmp_lt_u32_e32 vcc, s0, v72
	s_and_saveexec_b64 s[0:1], vcc
	s_xor_b64 s[0:1], exec, s[0:1]
	s_cbranch_execz .LBB0_62
	v_and_b32_e32 v6, 0x7fffffc0, v60
	v_and_b32_e32 v75, 0x3e0, v59
	v_add_u32_e32 v6, 0xffffb300, v6
	v_or_b32_e32 v12, v75, v5
	v_or_b32_e32 v26, v6, v2
	v_lshlrev_b32_e32 v12, 2, v12
	v_mov_b32_e32 v13, v7
	v_or_b32_e32 v28, 12, v26
	v_mov_b32_e32 v29, v7
	v_lshl_add_u64 v[12:13], s[8:9], 0, v[12:13]
	v_mov_b32_e32 v27, v7
	v_or_b32_e32 v22, 8, v26
	v_mov_b32_e32 v23, v7
	v_or_b32_e32 v24, 10, v26
	v_mov_b32_e32 v25, v7
	v_lshlrev_b64 v[28:29], 12, v[28:29]
	v_lshlrev_b64 v[14:15], 12, v[26:27]
	v_or_b32_e32 v16, 2, v26
	v_mov_b32_e32 v17, v7
	v_or_b32_e32 v18, 4, v26
	v_mov_b32_e32 v19, v7
	v_or_b32_e32 v20, 6, v26
	v_mov_b32_e32 v21, v7
	v_lshlrev_b64 v[22:23], 12, v[22:23]
	v_lshlrev_b64 v[24:25], 12, v[24:25]
	v_lshl_add_u64 v[76:77], v[12:13], 0, v[28:29]
	v_or_b32_e32 v28, 14, v26
	v_mov_b32_e32 v29, v7
	v_lshl_add_u64 v[14:15], v[12:13], 0, v[14:15]
	v_lshlrev_b64 v[16:17], 12, v[16:17]
	v_lshlrev_b64 v[18:19], 12, v[18:19]
	v_lshlrev_b64 v[20:21], 12, v[20:21]
	v_lshl_add_u64 v[22:23], v[12:13], 0, v[22:23]
	v_lshl_add_u64 v[24:25], v[12:13], 0, v[24:25]
	v_lshlrev_b64 v[28:29], 12, v[28:29]
	v_lshl_add_u64 v[16:17], v[12:13], 0, v[16:17]
	v_lshl_add_u64 v[18:19], v[12:13], 0, v[18:19]
	v_lshl_add_u64 v[20:21], v[12:13], 0, v[20:21]
	v_lshl_add_u64 v[78:79], v[12:13], 0, v[28:29]
	global_load_dword v91, v[14:15], off nt
	global_load_dword v92, v[16:17], off nt
	global_load_dword v93, v[18:19], off nt
	global_load_dword v28, v[20:21], off nt
	global_load_dword v29, v[22:23], off nt
	global_load_dword v89, v[24:25], off nt
	global_load_dword v90, v[76:77], off nt
	s_nop 0
	global_load_dword v24, v[78:79], off nt
	v_or_b32_e32 v22, 24, v26
	v_mov_b32_e32 v23, v7
	v_lshlrev_b64 v[22:23], 12, v[22:23]
	v_lshl_add_u64 v[76:77], v[12:13], 0, v[22:23]
	v_or_b32_e32 v22, 26, v26
	v_mov_b32_e32 v23, v7
	v_lshlrev_b64 v[22:23], 12, v[22:23]
	v_lshl_add_u64 v[78:79], v[12:13], 0, v[22:23]
	v_or_b32_e32 v22, 28, v26
	v_mov_b32_e32 v23, v7
	v_lshlrev_b64 v[22:23], 12, v[22:23]
	v_or_b32_e32 v14, 16, v26
	v_mov_b32_e32 v15, v7
	v_or_b32_e32 v20, 22, v26
	v_mov_b32_e32 v21, v7
	v_lshl_add_u64 v[80:81], v[12:13], 0, v[22:23]
	v_or_b32_e32 v22, 30, v26
	v_mov_b32_e32 v23, v7
	v_lshlrev_b64 v[14:15], 12, v[14:15]
	v_or_b32_e32 v16, 18, v26
	v_mov_b32_e32 v17, v7
	v_or_b32_e32 v18, 20, v26
	v_mov_b32_e32 v19, v7
	v_lshlrev_b64 v[20:21], 12, v[20:21]
	v_lshlrev_b64 v[22:23], 12, v[22:23]
	v_lshl_add_u64 v[14:15], v[12:13], 0, v[14:15]
	v_lshlrev_b64 v[16:17], 12, v[16:17]
	v_lshlrev_b64 v[18:19], 12, v[18:19]
	v_lshl_add_u64 v[20:21], v[12:13], 0, v[20:21]
	v_lshl_add_u64 v[82:83], v[12:13], 0, v[22:23]
	v_lshl_add_u64 v[16:17], v[12:13], 0, v[16:17]
	v_lshl_add_u64 v[18:19], v[12:13], 0, v[18:19]
	global_load_dword v25, v[14:15], off nt
	global_load_dword v87, v[16:17], off nt
	global_load_dword v88, v[18:19], off nt
	global_load_dword v22, v[20:21], off nt
	global_load_dword v23, v[76:77], off nt
	global_load_dword v85, v[78:79], off nt
	global_load_dword v86, v[80:81], off nt
	s_nop 0
	global_load_dword v20, v[82:83], off nt
	v_or_b32_e32 v82, 44, v26
	v_mov_b32_e32 v83, v7
	v_or_b32_e32 v14, 32, v26
	v_mov_b32_e32 v15, v7
	v_or_b32_e32 v16, 34, v26
	v_mov_b32_e32 v17, v7
	v_or_b32_e32 v18, 36, v26
	v_mov_b32_e32 v19, v7
	v_or_b32_e32 v78, 40, v26
	v_mov_b32_e32 v79, v7
	v_or_b32_e32 v80, 42, v26
	v_mov_b32_e32 v81, v7
	v_lshlrev_b64 v[82:83], 12, v[82:83]
	v_lshlrev_b64 v[14:15], 12, v[14:15]
	v_lshlrev_b64 v[16:17], 12, v[16:17]
	v_lshlrev_b64 v[18:19], 12, v[18:19]
	v_or_b32_e32 v76, 38, v26
	v_mov_b32_e32 v77, v7
	v_lshlrev_b64 v[78:79], 12, v[78:79]
	v_lshlrev_b64 v[80:81], 12, v[80:81]
	v_lshl_add_u64 v[94:95], v[12:13], 0, v[82:83]
	v_or_b32_e32 v82, 46, v26
	v_mov_b32_e32 v83, v7
	v_lshl_add_u64 v[14:15], v[12:13], 0, v[14:15]
	v_lshl_add_u64 v[16:17], v[12:13], 0, v[16:17]
	v_lshl_add_u64 v[18:19], v[12:13], 0, v[18:19]
	v_lshlrev_b64 v[76:77], 12, v[76:77]
	v_lshl_add_u64 v[78:79], v[12:13], 0, v[78:79]
	v_lshl_add_u64 v[80:81], v[12:13], 0, v[80:81]
	v_lshlrev_b64 v[82:83], 12, v[82:83]
	v_lshl_add_u64 v[76:77], v[12:13], 0, v[76:77]
	v_lshl_add_u64 v[96:97], v[12:13], 0, v[82:83]
	global_load_dword v21, v[14:15], off nt
	global_load_dword v83, v[16:17], off nt
	global_load_dword v84, v[18:19], off nt
	s_nop 0
	global_load_dword v18, v[76:77], off nt
	global_load_dword v19, v[78:79], off nt
	s_nop 0
	global_load_dword v81, v[80:81], off nt
	s_nop 0
	global_load_dword v82, v[94:95], off nt
	global_load_dword v16, v[96:97], off nt
	v_or_b32_e32 v78, 52, v26
	v_mov_b32_e32 v79, v7
	v_lshlrev_b64 v[78:79], 12, v[78:79]
	v_lshl_add_u64 v[94:95], v[12:13], 0, v[78:79]
	v_or_b32_e32 v78, 54, v26
	v_mov_b32_e32 v79, v7
	v_lshlrev_b64 v[78:79], 12, v[78:79]
	v_lshl_add_u64 v[96:97], v[12:13], 0, v[78:79]
	v_or_b32_e32 v78, 56, v26
	v_mov_b32_e32 v79, v7
	v_lshlrev_b64 v[78:79], 12, v[78:79]
	v_lshl_add_u64 v[98:99], v[12:13], 0, v[78:79]
	v_or_b32_e32 v78, 58, v26
	v_mov_b32_e32 v79, v7
	v_lshlrev_b64 v[78:79], 12, v[78:79]
	v_lshl_add_u64 v[100:101], v[12:13], 0, v[78:79]
	v_or_b32_e32 v78, 60, v26
	v_mov_b32_e32 v79, v7
	v_or_b32_e32 v14, 48, v26
	v_mov_b32_e32 v15, v7
	v_or_b32_e32 v76, 50, v26
	v_mov_b32_e32 v77, v7
	v_lshlrev_b64 v[78:79], 12, v[78:79]
	v_lshlrev_b64 v[14:15], 12, v[14:15]
	v_lshlrev_b64 v[76:77], 12, v[76:77]
	v_lshl_add_u64 v[102:103], v[12:13], 0, v[78:79]
	v_or_b32_e32 v78, 62, v26
	v_mov_b32_e32 v79, v7
	v_lshl_add_u64 v[14:15], v[12:13], 0, v[14:15]
	v_lshl_add_u64 v[76:77], v[12:13], 0, v[76:77]
	v_lshlrev_b64 v[78:79], 12, v[78:79]
	v_lshl_add_u64 v[104:105], v[12:13], 0, v[78:79]
	global_load_dword v17, v[14:15], off nt
	global_load_dword v79, v[76:77], off nt
	global_load_dword v80, v[94:95], off nt
	global_load_dword v12, v[96:97], off nt
	global_load_dword v13, v[98:99], off nt
	s_nop 0
	global_load_dword v77, v[100:101], off nt
	global_load_dword v78, v[102:103], off nt
	global_load_dword v76, v[104:105], off nt
	s_movk_i32 s30, 0x1ff
	v_cmp_lt_u32_e32 vcc, s30, v6
	s_or_b64 s[30:31], vcc, s[24:25]
	s_and_saveexec_b64 s[34:35], s[30:31]
	s_xor_b64 s[34:35], exec, s[34:35]
	s_cbranch_execz .LBB0_31
	v_add_u32_e32 v14, v30, v31
	s_waitcnt vmcnt(30)
	ds_write2_b32 v14, v91, v92 offset1:66
	s_waitcnt vmcnt(29)
	ds_write_b32 v14, v93 offset:528
;     ...
;     for (int i = 0; i < 32; ++i) { const int kk = 2 * i + (lane >> 5), k = k0 + kk; float v = wv[i] * cs; if (gain && k < gain_lim) v *= gain[k]; scr[kk * 33 + (lane & 31)] = v; }
.LBB0_31:
	s_or_saveexec_b64 s[34:35], s[34:35]
	v_add_u32_e32 v14, v6, v2
	s_xor_b64 exec, exec, s[34:35]
	s_cbranch_execz .LBB0_33
	v_lshl_add_u64 v[26:27], v[26:27], 2, s[18:19]
	v_mov_b32_e32 v15, v7
	v_lshl_add_u64 v[94:95], v[14:15], 2, s[18:19]
	global_load_dword v15, v[26:27], off nt
	global_load_dword v96, v[94:95], off offset:8 nt
	global_load_dword v97, v[94:95], off offset:16 nt
	s_nop 0
	global_load_dword v26, v[94:95], off offset:24 nt
	global_load_dword v27, v[94:95], off offset:32 nt
	v_add_u32_e32 v94, v30, v31
	s_waitcnt vmcnt(4)
	v_mul_f32_e32 v15, v91, v15
	s_waitcnt vmcnt(3)
	v_mul_f32_e32 v91, v92, v96
	s_waitcnt vmcnt(2)
	v_mul_f32_e32 v92, v93, v97
	ds_write2_b32 v94, v15, v91 offset1:66
	ds_write_b32 v94, v92 offset:528
	s_waitcnt vmcnt(0)
	v_pk_mul_f32 v[28:29], v[28:29], v[26:27]

;     ...
;     for (int i = 0; i < 32; ++i) { const int kk = 2 * i + (lane >> 5), k = k0 + kk; float v = wv[i] * cs; if (gain && k < gain_lim) v *= gain[k]; scr[kk * 33 + (lane & 31)] = v; }
.LBB0_35:
	s_andn2_saveexec_b64 s[34:35], s[34:35]
	s_cbranch_execz .LBB0_37
	v_mov_b32_e32 v15, v7
	v_lshl_add_u64 v[26:27], v[14:15], 2, s[18:19]
	global_load_dword v15, v[26:27], off offset:40 nt
	global_load_dword v91, v[26:27], off offset:48 nt
	global_load_dword v28, v[26:27], off offset:56 nt
	global_load_dword v29, v[26:27], off offset:64 nt
	v_add_u32_e32 v26, v30, v35
	s_waitcnt vmcnt(3)
	v_mul_f32_e32 v15, v89, v15
	s_waitcnt vmcnt(2)
	v_mul_f32_e32 v27, v90, v91
	ds_write2_b32 v26, v15, v27 offset1:66
	s_waitcnt vmcnt(0)
	v_pk_mul_f32 v[24:25], v[24:25], v[28:29]

;     ...
;     for (int i = 0; i < 32; ++i) { const int kk = 2 * i + (lane >> 5), k = k0 + kk; float v = wv[i] * cs; if (gain && k < gain_lim) v *= gain[k]; scr[kk * 33 + (lane & 31)] = v; }
.LBB0_39:
	s_andn2_saveexec_b64 s[34:35], s[34:35]
	s_cbranch_execz .LBB0_41
	v_mov_b32_e32 v15, v7
	v_lshl_add_u64 v[24:25], v[14:15], 2, s[18:19]
	global_load_dword v15, v[24:25], off offset:72 nt
	global_load_dword v28, v[24:25], off offset:80 nt
	global_load_dword v26, v[24:25], off offset:88 nt
	global_load_dword v27, v[24:25], off offset:96 nt
	v_add_u32_e32 v24, v30, v39
	s_waitcnt vmcnt(3)
	v_mul_f32_e32 v15, v87, v15
	s_waitcnt vmcnt(2)
	v_mul_f32_e32 v25, v88, v28
	ds_write2_b32 v24, v15, v25 offset1:66
	s_waitcnt vmcnt(0)
	v_pk_mul_f32 v[22:23], v[22:23], v[26:27]

;     ...
;     for (int i = 0; i < 32; ++i) { const int kk = 2 * i + (lane >> 5), k = k0 + kk; float v = wv[i] * cs; if (gain && k < gain_lim) v *= gain[k]; scr[kk * 33 + (lane & 31)] = v; }
.LBB0_43:
	s_andn2_saveexec_b64 s[34:35], s[34:35]
	s_cbranch_execz .LBB0_45
	v_mov_b32_e32 v15, v7
	v_lshl_add_u64 v[22:23], v[14:15], 2, s[18:19]
	global_load_dword v15, v[22:23], off offset:104 nt
	global_load_dword v26, v[22:23], off offset:112 nt
	global_load_dword v24, v[22:23], off offset:120 nt
	global_load_dword v25, v[22:23], off offset:128 nt
	v_add_u32_e32 v22, v30, v43
	s_waitcnt vmcnt(3)
	v_mul_f32_e32 v15, v85, v15
	s_waitcnt vmcnt(2)
	v_mul_f32_e32 v23, v86, v26
	ds_write2_b32 v22, v15, v23 offset1:66
	s_waitcnt vmcnt(0)
	v_pk_mul_f32 v[20:21], v[20:21], v[24:25]

;     ...
;     for (int i = 0; i < 32; ++i) { const int kk = 2 * i + (lane >> 5), k = k0 + kk; float v = wv[i] * cs; if (gain && k < gain_lim) v *= gain[k]; scr[kk * 33 + (lane & 31)] = v; }
.LBB0_47:
	s_andn2_saveexec_b64 s[34:35], s[34:35]
	s_cbranch_execz .LBB0_49
	v_mov_b32_e32 v15, v7
	v_lshl_add_u64 v[20:21], v[14:15], 2, s[18:19]
	global_load_dword v15, v[20:21], off offset:136 nt
	global_load_dword v24, v[20:21], off offset:144 nt
	global_load_dword v22, v[20:21], off offset:152 nt
	global_load_dword v23, v[20:21], off offset:160 nt
	v_add_u32_e32 v20, v30, v47
	s_waitcnt vmcnt(3)
	v_mul_f32_e32 v15, v83, v15
	s_waitcnt vmcnt(2)
	v_mul_f32_e32 v21, v84, v24
	ds_write2_b32 v20, v15, v21 offset1:66
	s_waitcnt vmcnt(0)
	v_pk_mul_f32 v[18:19], v[18:19], v[22:23]

;     ...
;     for (int i = 0; i < 32; ++i) { const int kk = 2 * i + (lane >> 5), k = k0 + kk; float v = wv[i] * cs; if (gain && k < gain_lim) v *= gain[k]; scr[kk * 33 + (lane & 31)] = v; }
.LBB0_51:
	s_andn2_saveexec_b64 s[34:35], s[34:35]
	s_cbranch_execz .LBB0_53
	v_mov_b32_e32 v15, v7
	v_lshl_add_u64 v[18:19], v[14:15], 2, s[18:19]
	global_load_dword v15, v[18:19], off offset:168 nt
	global_load_dword v22, v[18:19], off offset:176 nt
	global_load_dword v20, v[18:19], off offset:184 nt
	global_load_dword v21, v[18:19], off offset:192 nt
	v_add_u32_e32 v18, v30, v51
	s_waitcnt vmcnt(3)
	v_mul_f32_e32 v15, v81, v15
	s_waitcnt vmcnt(2)
	v_mul_f32_e32 v19, v82, v22
	ds_write2_b32 v18, v15, v19 offset1:66
	s_waitcnt vmcnt(0)
	v_pk_mul_f32 v[16:17], v[16:17], v[20:21]

;     ...
;     for (int i = 0; i < 32; ++i) { const int kk = 2 * i + (lane >> 5), k = k0 + kk; float v = wv[i] * cs; if (gain && k < gain_lim) v *= gain[k]; scr[kk * 33 + (lane & 31)] = v; }
.LBB0_55:
	s_andn2_saveexec_b64 s[34:35], s[34:35]
	s_cbranch_execz .LBB0_57
	v_mov_b32_e32 v15, v7
	v_lshl_add_u64 v[20:21], v[14:15], 2, s[18:19]
	global_load_dword v15, v[20:21], off offset:200 nt
	global_load_dword v17, v[20:21], off offset:208 nt
	global_load_dword v22, v[20:21], off offset:216 nt
	global_load_dword v23, v[20:21], off offset:224 nt
	s_waitcnt vmcnt(3)
	v_mul_f32_e32 v15, v79, v15
	s_waitcnt vmcnt(2)
	v_mul_f32_e32 v17, v80, v17
	ds_write2_b32 v16, v15, v17 offset0:70 offset1:136
	s_waitcnt vmcnt(0)
	v_pk_mul_f32 v[12:13], v[12:13], v[22:23]

;     ...
;     for (int i = 0; i < 32; ++i) { const int kk = 2 * i + (lane >> 5), k = k0 + kk; float v = wv[i] * cs; if (gain && k < gain_lim) v *= gain[k]; scr[kk * 33 + (lane & 31)] = v; }
.LBB0_59:
	s_andn2_saveexec_b64 s[30:31], s[30:31]
	s_cbranch_execz .LBB0_61
	v_mov_b32_e32 v15, v7
	v_lshl_add_u64 v[14:15], v[14:15], 2, s[18:19]
	global_load_dword v13, v[14:15], off offset:232 nt
	global_load_dword v16, v[14:15], off offset:240 nt
	s_nop 0
	global_load_dword v14, v[14:15], off offset:248 nt
	s_waitcnt vmcnt(2)
	v_mul_f32_e32 v13, v77, v13
	s_waitcnt vmcnt(1)
	v_mul_f32_e32 v15, v78, v16
	s_waitcnt vmcnt(0)
	v_mul_f32_e32 v76, v76, v14
	ds_write2_b32 v12, v13, v15 offset0:78 offset1:144

; #define LAS __attribute__((address_space(3)))
;     ...
;     for (int i = 0; i < 32; ++i) { const int k = k0 + 2 * i + (lane >> 5); wv[i] = W[(size_t)k * ldw + sc]; }
; #pragma unroll
;     for (int i = 0; i < 32; ++i) { const int kk = 2 * i + (lane >> 5), k = k0 + kk; float v = wv[i] * cs; if (gain && k < gain_lim) v *= gain[k]; scr[kk * 33 + (lane & 31)] = v; }
; __device__ __forceinline__ int win_srccol(int n) {
;     if (n < 640) { const int p = n & 63; if (p < 16) return (n - p) + ((p & 3) | ((p & 4) << 1) | ((p & 8) >> 1)); return n; }
;     if (n >= 768 && n < 1792) { const int p = (n - 768) & 127, q = p >> 3, nn = (p >> 2) & 1, j = p & 3; return (n - p) + nn * 64 + 4 * q + j; }
;     return n;
; }
; __device__ __forceinline__ void p0_prologue(const Params& p, LAS unsigned char* lds, int G) {
;     const int tid = threadIdx.x, lane = tid & 63, wave = tid >> 6;
;     LAS float* scr = (LAS float*)(lds + wave * 16384);
;     const int gw = blockIdx.x * 8 + wave, NGW = G * 8;
;     constexpr int I_GU = 16 * 176, I_D = 44 * 32, I_IN = 16 * 88, I_OUT = 16 * 32;
;     constexpr int NITEMS = 2 * I_GU + 2 * I_D + I_IN + I_OUT;
;     for (int it = gw; it < NITEMS; it += NGW) {
;         int r = it;
;         if (r < 2 * I_GU) {
;             const int which = r / I_GU; r -= which * I_GU; const int nb = r % 176, kb = r / 176, n0 = nb * 32;
;             const int pn = n0 >> 8, q = n0 & 255, bj = q >> 7, hid = pn * 128 + (q & 127) + (lane & 31);
;             const float* W = which == 0 ? (bj ? p.in[4] : p.in[3]) : (bj ? p.in[15] : p.in[14]);
;             p0_item(W, FF, hid, which == 0 ? nullptr : p.in[13], 1 << 30, (bf16_t*)(p.ws + (which == 0 ? WS_WGU1 : WS_WGU2)), D, n0, kb * 64, scr, lane, bj ? 0.6931471805599453f : 1.4426950408889634f); continue; }
;         r -= 2 * I_GU;
;         if (r < 2 * I_D) {
;             const int which = r / I_D; r -= which * I_D; const int nb = r % 32, kb = r / 32, n0 = nb * 32;
;             p0_item(which == 0 ? p.in[5] : p.in[16], D, n0 + (lane & 31), nullptr, 0, (bf16_t*)(p.ws + (which == 0 ? WS_WD1 : WS_WD2)), FF, n0, kb * 64, scr, lane); continue; }
;         r -= 2 * I_D;
;         if (r < I_IN) { const int nb = r % 88, kb = r / 88, n0 = nb * 32;
;             p0_item(p.in[7], DIN, win_srccol(n0 + (lane & 31)), p.in[6], 1 << 30, (bf16_t*)(p.ws + WS_WIN), D, n0, kb * 64, scr, lane); continue; }
.LBB0_62:
	s_andn2_saveexec_b64 s[30:31], s[0:1]
	s_cbranch_execz .LBB0_160
	v_add_u16_e32 v6, 0xdf00, v72
	v_mul_u32_u24_e32 v12, 0xba2f, v6
	v_lshrrev_b32_e32 v12, 22, v12
	v_mul_lo_u16_e32 v13, 0x58, v12
	v_sub_u16_e32 v6, v6, v13
	v_lshlrev_b16_e32 v75, 5, v6
	v_or_b32_e32 v13, v5, v75
	v_cmp_lt_u16_e32 vcc, 19, v6
	s_and_saveexec_b64 s[0:1], vcc
	s_xor_b64 s[0:1], exec, s[0:1]
	v_lshrrev_b32_e32 v14, 1, v13
	v_add_u16_e32 v6, 0xfd00, v75
	v_and_b32_e32 v14, 60, v14
	v_and_b32_e32 v15, 0x783, v13
	s_movk_i32 s34, 0x400
	v_or3_b32 v14, v15, v57, v14
	v_cmp_gt_u16_e32 vcc, s34, v6
	s_nop 1
	v_cndmask_b32_e32 v6, v13, v14, vcc
	s_andn2_saveexec_b64 s[0:1], s[0:1]
	v_and_b32_e32 v6, 48, v13
	s_movk_i32 s34, 0x3c3
	v_and_or_b32 v14, v13, s34, v58
	v_cmp_eq_u32_e32 vcc, 0, v6
	s_nop 1
	v_cndmask_b32_e32 v6, v13, v14, vcc
	s_or_b64 exec, exec, s[0:1]
	v_lshlrev_b16_e32 v76, 6, v12
	v_or_b32_e32 v28, v2, v76
	v_lshl_add_u64 v[12:13], v[6:7], 2, s[6:7]
	v_mul_u32_u24_e32 v6, 0xb00, v28
	s_movk_i32 s0, 0x2c00
	v_lshlrev_b32_e32 v6, 2, v6
	v_mad_u64_u32 v[14:15], s[0:1], v28, s0, v[12:13]
	v_lshl_add_u64 v[12:13], v[12:13], 0, v[6:7]
	v_add_co_u32_e32 v16, vcc, 0x5000, v12
	v_cndmask_b32_e64 v29, 0, 1, s[20:21]
	s_nop 0
	v_addc_co_u32_e32 v17, vcc, 0, v13, vcc
	v_add_co_u32_e32 v18, vcc, 0xb000, v12
	v_cmp_ne_u32_e64 s[0:1], 1, v29
	s_nop 0
	v_addc_co_u32_e32 v19, vcc, 0, v13, vcc
	v_add_co_u32_e32 v20, vcc, 0x10000, v12
	s_nop 1
	v_addc_co_u32_e32 v21, vcc, 0, v13, vcc
	v_add_co_u32_e32 v22, vcc, 0x16000, v12
	s_nop 1
	v_addc_co_u32_e32 v23, vcc, 0, v13, vcc
	v_add_co_u32_e32 v24, vcc, 0x1b000, v12
	s_nop 1
	v_addc_co_u32_e32 v25, vcc, 0, v13, vcc
	v_add_co_u32_e32 v78, vcc, 0x21000, v12
	s_nop 1
	v_addc_co_u32_e32 v79, vcc, 0, v13, vcc
	v_add_co_u32_e32 v80, vcc, 0x26000, v12
	s_nop 1
	v_addc_co_u32_e32 v81, vcc, 0, v13, vcc
	global_load_dword v91, v[14:15], off nt
	global_load_dword v92, v[16:17], off offset:2048 nt
	global_load_dword v26, v[18:19], off nt
	global_load_dword v27, v[20:21], off offset:2048 nt
	global_load_dword v87, v[22:23], off nt
	global_load_dword v88, v[24:25], off offset:2048 nt
	s_nop 0
	global_load_dword v22, v[78:79], off nt
	global_load_dword v23, v[80:81], off offset:2048 nt
	v_add_co_u32_e32 v14, vcc, 0x2c000, v12
	s_nop 1
	v_addc_co_u32_e32 v15, vcc, 0, v13, vcc
	v_add_co_u32_e32 v16, vcc, 0x31000, v12
	s_nop 1
	v_addc_co_u32_e32 v17, vcc, 0, v13, vcc
	v_add_co_u32_e32 v18, vcc, 0x37000, v12
	s_nop 1
	v_addc_co_u32_e32 v19, vcc, 0, v13, vcc
	v_add_co_u32_e32 v20, vcc, 0x3c000, v12
	s_nop 1
	v_addc_co_u32_e32 v21, vcc, 0, v13, vcc
	v_add_co_u32_e32 v78, vcc, 0x42000, v12
	s_nop 1
	v_addc_co_u32_e32 v79, vcc, 0, v13, vcc
	v_add_co_u32_e32 v80, vcc, 0x47000, v12
	s_nop 1
	v_addc_co_u32_e32 v81, vcc, 0, v13, vcc
	v_add_co_u32_e32 v94, vcc, 0x4d000, v12
	s_nop 1
	v_addc_co_u32_e32 v95, vcc, 0, v13, vcc
	v_add_co_u32_e32 v96, vcc, 0x52000, v12
	s_nop 1
	v_addc_co_u32_e32 v97, vcc, 0, v13, vcc
	global_load_dword v89, v[14:15], off nt
	global_load_dword v90, v[16:17], off offset:2048 nt
	global_load_dword v24, v[18:19], off nt
	global_load_dword v25, v[20:21], off offset:2048 nt
	global_load_dword v83, v[78:79], off nt
	global_load_dword v84, v[80:81], off offset:2048 nt
	s_nop 0
	global_load_dword v18, v[94:95], off nt
	global_load_dword v19, v[96:97], off offset:2048 nt
	v_add_co_u32_e32 v14, vcc, 0x58000, v12
	s_nop 1
	v_addc_co_u32_e32 v15, vcc, 0, v13, vcc
	v_add_co_u32_e32 v16, vcc, 0x5d000, v12
	s_nop 1
	v_addc_co_u32_e32 v17, vcc, 0, v13, vcc
	v_add_co_u32_e32 v20, vcc, 0x63000, v12
	s_nop 1
	v_addc_co_u32_e32 v21, vcc, 0, v13, vcc
	v_add_co_u32_e32 v78, vcc, 0x68000, v12
	s_nop 1
	v_addc_co_u32_e32 v79, vcc, 0, v13, vcc
	v_add_co_u32_e32 v80, vcc, 0x6e000, v12
	s_nop 1
	v_addc_co_u32_e32 v81, vcc, 0, v13, vcc
	v_add_co_u32_e32 v94, vcc, 0x73000, v12
	s_nop 1
	v_addc_co_u32_e32 v95, vcc, 0, v13, vcc
	v_add_co_u32_e32 v96, vcc, 0x79000, v12
	s_nop 1
	v_addc_co_u32_e32 v97, vcc, 0, v13, vcc
	v_add_co_u32_e32 v98, vcc, 0x7e000, v12
	s_nop 1
	v_addc_co_u32_e32 v99, vcc, 0, v13, vcc
	global_load_dword v85, v[14:15], off nt
	global_load_dword v86, v[16:17], off offset:2048 nt
	s_nop 0
	global_load_dword v20, v[20:21], off nt
	s_nop 0
	global_load_dword v21, v[78:79], off offset:2048 nt
	s_nop 0
	global_load_dword v78, v[80:81], off nt
	global_load_dword v79, v[94:95], off offset:2048 nt
	global_load_dword v14, v[96:97], off nt
	global_load_dword v15, v[98:99], off offset:2048 nt
	v_add_co_u32_e32 v16, vcc, 0x84000, v12
	v_add_lshl_u32 v80, v2, v76, 2
	s_nop 0
	v_addc_co_u32_e32 v17, vcc, 0, v13, vcc
	v_add_co_u32_e32 v94, vcc, 0x89000, v12
	s_nop 1
	v_addc_co_u32_e32 v95, vcc, 0, v13, vcc
	v_add_co_u32_e32 v96, vcc, 0x8f000, v12
	s_nop 1
	v_addc_co_u32_e32 v97, vcc, 0, v13, vcc
	v_add_co_u32_e32 v98, vcc, 0x94000, v12
	s_nop 1
	v_addc_co_u32_e32 v99, vcc, 0, v13, vcc
	v_add_co_u32_e32 v100, vcc, 0x9a000, v12
	s_nop 1
	v_addc_co_u32_e32 v101, vcc, 0, v13, vcc
	v_add_co_u32_e32 v102, vcc, 0x9f000, v12
	s_nop 1
	v_addc_co_u32_e32 v103, vcc, 0, v13, vcc
	v_add_co_u32_e32 v104, vcc, 0xa5000, v12
	s_nop 1
	v_addc_co_u32_e32 v105, vcc, 0, v13, vcc
	v_add_co_u32_e32 v106, vcc, 0xaa000, v12
	s_nop 1
	v_addc_co_u32_e32 v107, vcc, 0, v13, vcc
	global_load_dword v81, v[16:17], off nt
	global_load_dword v82, v[94:95], off offset:2048 nt
	s_nop 0
	global_load_dword v16, v[96:97], off nt
	global_load_dword v17, v[98:99], off offset:2048 nt
	global_load_dword v6, v[100:101], off nt
	global_load_dword v77, v[102:103], off offset:2048 nt
	global_load_dword v12, v[104:105], off nt
	global_load_dword v13, v[106:107], off offset:2048 nt
	s_andn2_b64 vcc, exec, s[20:21]
	s_cbranch_vccnz .LBB0_161
	v_lshlrev_b32_e32 v93, 2, v28
	global_load_dword v94, v80, s[4:5] offset:8
	global_load_dword v28, v80, s[4:5] offset:16
	global_load_dword v29, v80, s[4:5] offset:24
	s_nop 0
	global_load_dword v93, v93, s[4:5]
	v_add_u32_e32 v95, v30, v31
	s_waitcnt vmcnt(3)
	v_mul_f32_e32 v94, v92, v94
	s_waitcnt vmcnt(1)
	v_pk_mul_f32 v[28:29], v[26:27], v[28:29]
	s_waitcnt vmcnt(0)
	v_mul_f32_e32 v93, v91, v93
	ds_write2_b32 v95, v93, v94 offset1:66
	s_cbranch_execnz .LBB0_70

;     ...
;     for (int i = 0; i < 32; ++i) { const int k = k0 + 2 * i + (lane >> 5); wv[i] = W[(size_t)k * ldw + sc]; }
; #pragma unroll
;     for (int i = 0; i < 32; ++i) { const int kk = 2 * i + (lane >> 5), k = k0 + kk; float v = wv[i] * cs; if (gain && k < gain_lim) v *= gain[k]; scr[kk * 33 + (lane & 31)] = v; }
; __device__ __forceinline__ void p0_prologue(const Params& p, LAS unsigned char* lds, int G) {
;     ...
;         if (r < 2 * I_D) {
;             const int which = r / I_D; r -= which * I_D; const int nb = r % 32, kb = r / 32, n0 = nb * 32;
;             p0_item(which == 0 ? p.in[5] : p.in[16], D, n0 + (lane & 31), nullptr, 0, (bf16_t*)(p.ws + (which == 0 ? WS_WD1 : WS_WD2)), FF, n0, kb * 64, scr, lane); continue; }
.LBB0_93:
	v_add_u32_e32 v6, 0xffffea00, v72
	v_cmp_gt_u32_e32 vcc, s54, v6
	v_mov_b32_e32 v13, v7
	s_nop 0
	v_cndmask_b32_e64 v12, v63, 40, vcc
	v_lshl_add_u64 v[12:13], s[88:89], 0, v[12:13]
	global_load_dwordx2 v[14:15], v[12:13], off nt
	v_add_u32_e32 v12, 0xffffe480, v72
	v_cndmask_b32_e32 v12, v12, v6, vcc
	v_lshlrev_b32_e32 v16, 5, v12
	v_cndmask_b32_e32 v6, v61, v62, vcc
	v_lshlrev_b32_e32 v17, 1, v12
	v_and_b32_e32 v75, 0x3e0, v16
	v_lshl_add_u64 v[12:13], s[92:93], 0, v[6:7]
	v_and_b32_e32 v92, 0xfc0, v17
	v_or_b32_e32 v6, v75, v5
	v_or_b32_e32 v16, v92, v2
	v_lshlrev_b32_e32 v6, 2, v6
	s_waitcnt vmcnt(0)
	v_lshl_add_u64 v[14:15], v[14:15], 0, v[6:7]
	v_lshlrev_b32_e32 v6, 12, v16
	v_lshl_add_u64 v[14:15], v[14:15], 0, v[6:7]
	v_add_co_u32_e32 v16, vcc, s55, v14
	s_nop 1
	v_addc_co_u32_e32 v17, vcc, 0, v15, vcc
	v_add_co_u32_e32 v18, vcc, s56, v14
	s_nop 1
	v_addc_co_u32_e32 v19, vcc, 0, v15, vcc
	v_add_co_u32_e32 v20, vcc, s57, v14
	s_nop 1
	v_addc_co_u32_e32 v21, vcc, 0, v15, vcc
	v_add_co_u32_e32 v22, vcc, s58, v14
	s_nop 1
	v_addc_co_u32_e32 v23, vcc, 0, v15, vcc
	v_add_co_u32_e32 v24, vcc, s59, v14
	s_nop 1
	v_addc_co_u32_e32 v25, vcc, 0, v15, vcc
	v_add_co_u32_e32 v26, vcc, s60, v14
	s_nop 1
	v_addc_co_u32_e32 v27, vcc, 0, v15, vcc
	v_add_co_u32_e32 v28, vcc, s61, v14
	s_nop 1
	v_addc_co_u32_e32 v29, vcc, 0, v15, vcc
	v_add_co_u32_e32 v76, vcc, s41, v14
	s_nop 1
	v_addc_co_u32_e32 v77, vcc, 0, v15, vcc
	v_add_co_u32_e32 v78, vcc, s62, v14
	s_nop 1
	v_addc_co_u32_e32 v79, vcc, 0, v15, vcc
	v_add_co_u32_e32 v80, vcc, s63, v14
	s_nop 1
	v_addc_co_u32_e32 v81, vcc, 0, v15, vcc
	v_add_co_u32_e32 v82, vcc, s42, v14
	s_nop 1
	v_addc_co_u32_e32 v83, vcc, 0, v15, vcc
	v_add_co_u32_e32 v84, vcc, s64, v14
	s_nop 1
	v_addc_co_u32_e32 v85, vcc, 0, v15, vcc
	v_add_co_u32_e32 v86, vcc, s65, v14
	s_nop 1
	v_addc_co_u32_e32 v87, vcc, 0, v15, vcc
	v_add_co_u32_e32 v88, vcc, s66, v14
	s_nop 1
	v_addc_co_u32_e32 v89, vcc, 0, v15, vcc
	v_add_co_u32_e32 v90, vcc, s67, v14
	s_nop 1
	v_addc_co_u32_e32 v91, vcc, 0, v15, vcc
	global_load_dword v6, v[14:15], off nt
	global_load_dword v93, v[16:17], off nt
	global_load_dword v94, v[18:19], off nt
	global_load_dword v95, v[20:21], off nt
	global_load_dword v96, v[22:23], off nt
	global_load_dword v97, v[24:25], off nt
	global_load_dword v98, v[26:27], off nt
	global_load_dword v99, v[28:29], off nt
	global_load_dword v100, v[76:77], off nt
	s_nop 0
	global_load_dword v78, v[78:79], off nt
	s_nop 0
	global_load_dword v79, v[80:81], off nt
	s_nop 0
	global_load_dword v80, v[82:83], off nt
	global_load_dword v81, v[84:85], off nt
	s_nop 0
	global_load_dword v82, v[86:87], off nt
	global_load_dword v83, v[88:89], off nt
	global_load_dword v84, v[90:91], off nt
	v_add_co_u32_e32 v16, vcc, s68, v14
	s_nop 1
	v_addc_co_u32_e32 v17, vcc, 0, v15, vcc
	v_add_co_u32_e32 v18, vcc, s69, v14
	s_nop 1
	v_addc_co_u32_e32 v19, vcc, 0, v15, vcc
	v_add_co_u32_e32 v20, vcc, s70, v14
	s_nop 1
	v_addc_co_u32_e32 v21, vcc, 0, v15, vcc
	v_add_co_u32_e32 v22, vcc, s43, v14
	s_nop 1
	v_addc_co_u32_e32 v23, vcc, 0, v15, vcc
	v_add_co_u32_e32 v24, vcc, s71, v14
	s_nop 1
	v_addc_co_u32_e32 v25, vcc, 0, v15, vcc
	v_add_co_u32_e32 v26, vcc, s72, v14
	s_nop 1
	v_addc_co_u32_e32 v27, vcc, 0, v15, vcc
	v_add_co_u32_e32 v28, vcc, s44, v14
	s_nop 1
	v_addc_co_u32_e32 v29, vcc, 0, v15, vcc
	v_add_co_u32_e32 v76, vcc, s73, v14
	s_nop 1
	v_addc_co_u32_e32 v77, vcc, 0, v15, vcc
	global_load_dword v85, v[16:17], off nt
	global_load_dword v86, v[18:19], off nt
	global_load_dword v87, v[20:21], off nt
	global_load_dword v88, v[22:23], off nt
	global_load_dword v89, v[24:25], off nt
	global_load_dword v90, v[26:27], off nt
	global_load_dword v91, v[28:29], off nt
	s_nop 0
	global_load_dword v76, v[76:77], off nt
	v_add_co_u32_e32 v16, vcc, s74, v14
	s_nop 1
	v_addc_co_u32_e32 v17, vcc, 0, v15, vcc
	v_add_co_u32_e32 v18, vcc, s75, v14
	s_nop 1
	v_addc_co_u32_e32 v19, vcc, 0, v15, vcc
	v_add_co_u32_e32 v20, vcc, s76, v14
	s_nop 1
	v_addc_co_u32_e32 v21, vcc, 0, v15, vcc
	v_add_co_u32_e32 v22, vcc, s77, v14
	s_nop 1
	v_addc_co_u32_e32 v23, vcc, 0, v15, vcc
	v_add_co_u32_e32 v24, vcc, s78, v14
	s_nop 1
	v_addc_co_u32_e32 v25, vcc, 0, v15, vcc
	v_add_co_u32_e32 v26, vcc, s79, v14
	s_nop 1
	v_addc_co_u32_e32 v27, vcc, 0, v15, vcc
	v_add_co_u32_e32 v28, vcc, s45, v14
	s_nop 1
	v_addc_co_u32_e32 v29, vcc, 0, v15, vcc
	v_add_co_u32_e32 v14, vcc, s80, v14
	s_nop 1
	v_addc_co_u32_e32 v15, vcc, 0, v15, vcc
	global_load_dword v16, v[16:17], off nt
	s_nop 0
	global_load_dword v17, v[18:19], off nt
	s_nop 0
	global_load_dword v18, v[20:21], off nt
	global_load_dword v19, v[22:23], off nt
	s_nop 0
	global_load_dword v20, v[24:25], off nt
	global_load_dword v21, v[26:27], off nt
	global_load_dword v22, v[28:29], off nt
	s_nop 0
	global_load_dword v14, v[14:15], off nt
	v_add_u32_e32 v15, v30, v31
	s_waitcnt vmcnt(30)
	ds_write2_b32 v15, v6, v93 offset1:66
	s_waitcnt vmcnt(28)
	ds_write2_b32 v15, v94, v95 offset0:132 offset1:198
	v_add_u32_e32 v6, 0x400, v15
	s_waitcnt vmcnt(26)
	ds_write2_b32 v6, v96, v97 offset0:8 offset1:74
	s_waitcnt vmcnt(24)
	ds_write2_b32 v6, v98, v99 offset0:140 offset1:206
	v_add_u32_e32 v6, 0x800, v15
	s_waitcnt vmcnt(22)
	ds_write2_b32 v6, v100, v78 offset0:16 offset1:82
	s_waitcnt vmcnt(20)
	ds_write2_b32 v6, v79, v80 offset0:148 offset1:214
	v_add_u32_e32 v6, 0xc00, v15
	s_waitcnt vmcnt(18)
	ds_write2_b32 v6, v81, v82 offset0:24 offset1:90
	s_waitcnt vmcnt(16)
	ds_write2_b32 v6, v83, v84 offset0:156 offset1:222
	v_add_u32_e32 v6, 0x1000, v15
	s_waitcnt vmcnt(14)
; #define LAS __attribute__((address_space(3)))
; __device__ __forceinline__ unsigned pk2(float lo, float hi) { return f2bf(lo) | (f2bf(hi) << 16); }
;     ...
;     asm volatile("s_waitcnt lgkmcnt(0)" ::: "memory");
;     const int c = lane & 7;
; #pragma unroll
;     for (int j = 0; j < 4; ++j) { const int n = (lane >> 3) + 8 * j; const LAS float* s = scr + (8 * c) * 33 + n;
;         u32x4 o; o.x = pk2(s[0 * 33], s[1 * 33]); o.y = pk2(s[2 * 33], s[3 * 33]); o.z = pk2(s[4 * 33], s[5 * 33]); o.w = pk2(s[6 * 33], s[7 * 33]);
;         *(u32x4*)(WT + (size_t)(n0 + n) * K + k0 + 8 * c) = o; }
;     asm volatile("s_waitcnt lgkmcnt(0)" ::: "memory");
	ds_write2_b32 v6, v85, v86 offset0:32 offset1:98
	s_waitcnt vmcnt(12)
	ds_write2_b32 v6, v87, v88 offset0:164 offset1:230
	v_add_u32_e32 v6, 0x1400, v15
	s_waitcnt vmcnt(10)
	ds_write2_b32 v6, v89, v90 offset0:40 offset1:106
	s_waitcnt vmcnt(8)
	ds_write2_b32 v6, v91, v76 offset0:172 offset1:238
	v_add_u32_e32 v6, 0x1800, v15
	s_waitcnt vmcnt(6)
	ds_write2_b32 v6, v16, v17 offset0:48 offset1:114
	s_waitcnt vmcnt(4)
	ds_write2_b32 v6, v18, v19 offset0:180 offset1:246
	v_add_u32_e32 v6, 0x1c00, v15
	s_waitcnt vmcnt(2)
	ds_write2_b32 v6, v20, v21 offset0:56 offset1:122
	s_waitcnt vmcnt(0)
	ds_write2_b32 v6, v22, v14 offset0:188 offset1:254
	s_waitcnt lgkmcnt(0)
	ds_read2_b32 v[16:17], v74 offset1:8
	ds_read2_b32 v[20:21], v74 offset0:33 offset1:41
	v_lshlrev_b32_e32 v6, 1, v92
	ds_read2_b32 v[22:23], v74 offset0:66 offset1:74
	v_lshl_add_u64 v[12:13], v[12:13], 0, v[6:7]
	v_lshlrev_b32_e32 v6, 1, v4
	ds_read2_b32 v[24:25], v74 offset0:99 offset1:107
	v_lshl_add_u64 v[18:19], v[12:13], 0, v[6:7]
	s_waitcnt lgkmcnt(3)
	v_bfe_u32 v6, v16, 16, 1
	v_add3_u32 v6, v16, v6, s39
	s_waitcnt lgkmcnt(2)
	v_bfe_u32 v12, v20, 16, 1
	ds_read2_b32 v[26:27], v74 offset0:132 offset1:140
	v_lshrrev_b32_e32 v6, 16, v6
	v_add3_u32 v12, v20, v12, s39
	ds_read2_b32 v[28:29], v74 offset0:165 offset1:173
	v_and_or_b32 v12, v12, s40, v6
	s_waitcnt lgkmcnt(3)
	v_bfe_u32 v6, v22, 16, 1
	v_add3_u32 v6, v22, v6, s39
	s_waitcnt lgkmcnt(2)
	v_bfe_u32 v13, v24, 16, 1
	ds_read2_b32 v[76:77], v74 offset0:198 offset1:206
	v_lshrrev_b32_e32 v6, 16, v6
	v_add3_u32 v13, v24, v13, s39
	ds_read2_b32 v[78:79], v74 offset0:231 offset1:239
	v_and_or_b32 v13, v13, s40, v6
	s_waitcnt lgkmcnt(3)
	v_bfe_u32 v6, v26, 16, 1
	v_add3_u32 v6, v26, v6, s39
	s_waitcnt lgkmcnt(2)
	v_bfe_u32 v14, v28, 16, 1
	v_lshrrev_b32_e32 v6, 16, v6
	v_add3_u32 v14, v28, v14, s39
	v_and_or_b32 v14, v14, s40, v6
	s_waitcnt lgkmcnt(1)
	v_bfe_u32 v6, v76, 16, 1
	v_add3_u32 v6, v76, v6, s39
	s_waitcnt lgkmcnt(0)
	v_bfe_u32 v15, v78, 16, 1
	v_lshrrev_b32_e32 v6, 16, v6
	v_add3_u32 v15, v78, v15, s39
	v_and_or_b32 v15, v15, s40, v6
	v_or_b32_e32 v6, v75, v53
	v_mul_u32_u24_e32 v6, 0xb00, v6
	v_lshlrev_b32_e32 v6, 1, v6
	v_lshl_add_u64 v[80:81], v[18:19], 0, v[6:7]
	v_bfe_u32 v6, v17, 16, 1
	global_store_dwordx4 v[80:81], v[12:15], off
	v_add3_u32 v6, v17, v6, s39
	v_lshrrev_b32_e32 v6, 16, v6
	v_bfe_u32 v12, v21, 16, 1
	v_add3_u32 v12, v21, v12, s39
	v_and_or_b32 v12, v12, s40, v6
	v_bfe_u32 v6, v23, 16, 1
	v_add3_u32 v6, v23, v6, s39
	v_bfe_u32 v13, v25, 16, 1
	v_lshrrev_b32_e32 v6, 16, v6
	v_add3_u32 v13, v25, v13, s39
	v_and_or_b32 v13, v13, s40, v6
	v_bfe_u32 v6, v27, 16, 1
	v_add3_u32 v6, v27, v6, s39
	v_bfe_u32 v14, v29, 16, 1
	v_lshrrev_b32_e32 v6, 16, v6
	v_add3_u32 v14, v29, v14, s39
	v_and_or_b32 v14, v14, s40, v6
	v_bfe_u32 v6, v77, 16, 1
	v_add3_u32 v6, v77, v6, s39
	v_bfe_u32 v15, v79, 16, 1
	v_lshrrev_b32_e32 v6, 16, v6
	v_add3_u32 v15, v79, v15, s39
	v_and_or_b32 v15, v15, s40, v6
	v_or_b32_e32 v6, v75, v54
	v_mul_u32_u24_e32 v6, 0xb00, v6
	v_lshlrev_b32_e32 v6, 1, v6
	ds_read2_b32 v[16:17], v74 offset0:16 offset1:24
	v_lshl_add_u64 v[20:21], v[18:19], 0, v[6:7]
	global_store_dwordx4 v[20:21], v[12:15], off
	ds_read2_b32 v[20:21], v74 offset0:49 offset1:57
	ds_read2_b32 v[22:23], v74 offset0:82 offset1:90
	ds_read2_b32 v[24:25], v74 offset0:115 offset1:123
	s_waitcnt lgkmcnt(3)
	v_bfe_u32 v6, v16, 16, 1
	v_add3_u32 v6, v16, v6, s39
	s_waitcnt lgkmcnt(2)
	v_bfe_u32 v12, v20, 16, 1
	ds_read2_b32 v[26:27], v74 offset0:148 offset1:156
	v_lshrrev_b32_e32 v6, 16, v6
	v_add3_u32 v12, v20, v12, s39
	ds_read2_b32 v[28:29], v74 offset0:181 offset1:189
	v_and_or_b32 v12, v12, s40, v6
	s_waitcnt lgkmcnt(3)
	v_bfe_u32 v6, v22, 16, 1
	v_add3_u32 v6, v22, v6, s39
	s_waitcnt lgkmcnt(2)
	v_bfe_u32 v13, v24, 16, 1
	ds_read2_b32 v[76:77], v74 offset0:214 offset1:222
	v_lshrrev_b32_e32 v6, 16, v6
	v_add3_u32 v13, v24, v13, s39
	ds_read2_b32 v[78:79], v74 offset0:247 offset1:255
	v_and_or_b32 v13, v13, s40, v6
	s_waitcnt lgkmcnt(3)
	v_bfe_u32 v6, v26, 16, 1
	v_add3_u32 v6, v26, v6, s39
	s_waitcnt lgkmcnt(2)
	v_bfe_u32 v14, v28, 16, 1
	v_lshrrev_b32_e32 v6, 16, v6
	v_add3_u32 v14, v28, v14, s39
	v_and_or_b32 v14, v14, s40, v6
	s_waitcnt lgkmcnt(1)
	v_bfe_u32 v6, v76, 16, 1
	v_add3_u32 v6, v76, v6, s39
	s_waitcnt lgkmcnt(0)
	v_bfe_u32 v15, v78, 16, 1
	v_lshrrev_b32_e32 v6, 16, v6
	v_add3_u32 v15, v78, v15, s39
	v_and_or_b32 v15, v15, s40, v6
	v_or_b32_e32 v6, v75, v55
	v_mul_u32_u24_e32 v6, 0xb00, v6
	v_lshlrev_b32_e32 v6, 1, v6
	v_lshl_add_u64 v[80:81], v[18:19], 0, v[6:7]
	v_bfe_u32 v6, v17, 16, 1
	global_store_dwordx4 v[80:81], v[12:15], off
	v_add3_u32 v6, v17, v6, s39
	v_lshrrev_b32_e32 v6, 16, v6
	v_bfe_u32 v12, v21, 16, 1
	v_add3_u32 v12, v21, v12, s39
	v_and_or_b32 v12, v12, s40, v6
	v_bfe_u32 v6, v23, 16, 1
	v_add3_u32 v6, v23, v6, s39
	v_bfe_u32 v13, v25, 16, 1
	v_lshrrev_b32_e32 v6, 16, v6
	v_add3_u32 v13, v25, v13, s39
	v_and_or_b32 v13, v13, s40, v6
	v_bfe_u32 v6, v27, 16, 1
	v_add3_u32 v6, v27, v6, s39
	v_bfe_u32 v14, v29, 16, 1
	v_lshrrev_b32_e32 v6, 16, v6
	v_add3_u32 v14, v29, v14, s39
	v_and_or_b32 v14, v14, s40, v6
	v_bfe_u32 v6, v77, 16, 1
	v_add3_u32 v6, v77, v6, s39
	v_bfe_u32 v15, v79, 16, 1
	v_lshrrev_b32_e32 v6, 16, v6
	v_add3_u32 v15, v79, v15, s39
	v_and_or_b32 v15, v15, s40, v6
	v_or_b32_e32 v6, v75, v56
	v_mul_u32_u24_e32 v6, 0xb00, v6
	v_lshlrev_b32_e32 v6, 1, v6
	v_lshl_add_u64 v[16:17], v[18:19], 0, v[6:7]
	global_store_dwordx4 v[16:17], v[12:15], off
	s_waitcnt lgkmcnt(0)

;     ...
;     for (int i = 0; i < 32; ++i) { const int k = k0 + 2 * i + (lane >> 5); wv[i] = W[(size_t)k * ldw + sc]; }
; #pragma unroll
;     for (int i = 0; i < 32; ++i) { const int kk = 2 * i + (lane >> 5), k = k0 + kk; float v = wv[i] * cs; if (gain && k < gain_lim) v *= gain[k]; scr[kk * 33 + (lane & 31)] = v; }
; __device__ __forceinline__ void p0_prologue(const Params& p, LAS unsigned char* lds, int G) {
;     ...
;         int r = it;
;         if (r < 2 * I_GU) {
;             const int which = r / I_GU; r -= which * I_GU; const int nb = r % 176, kb = r / 176, n0 = nb * 32;
;             const int pn = n0 >> 8, q = n0 & 255, bj = q >> 7, hid = pn * 128 + (q & 127) + (lane & 31);
;             const float* W = which == 0 ? (bj ? p.in[4] : p.in[3]) : (bj ? p.in[15] : p.in[14]);
;             p0_item(W, FF, hid, which == 0 ? nullptr : p.in[13], 1 << 30, (bf16_t*)(p.ws + (which == 0 ? WS_WGU1 : WS_WGU2)), D, n0, kb * 64, scr, lane, bj ? 0.6931471805599453f : 1.4426950408889634f); continue; }
.LBB0_95:
	s_andn2_saveexec_b64 s[28:29], s[2:3]
	s_cbranch_execz .LBB0_25
	v_mul_hi_i32 v6, v72, s81
	v_lshrrev_b32_e32 v12, 31, v6
	v_ashrrev_i32_e32 v6, 9, v6
	v_add_u32_e32 v6, v6, v12
	v_mul_i32_i24_e32 v6, 0xb00, v6
	v_sub_u32_e32 v6, v72, v6
	v_mul_i32_i24_sdwa v12, sext(v6), s82 dst_sel:DWORD dst_unused:UNUSED_PAD src0_sel:WORD_0 src1_sel:DWORD
	v_lshrrev_b32_e32 v13, 31, v12
	v_ashrrev_i32_e32 v12, 19, v12
	v_add_u16_e32 v14, v12, v13
	v_mul_lo_u16_e32 v12, 0xb0, v14
	v_sub_u16_e32 v15, v6, v12
	v_and_b32_e32 v12, 4, v15
	v_add_u32_e32 v6, 0xaff, v72
	v_cmp_eq_u16_e64 s[2:3], 0, v12
	v_cmp_gt_u32_e64 s[0:1], s38, v6
	v_lshlrev_b32_sdwa v18, v64, sext(v15) dst_sel:DWORD dst_unused:UNUSED_PAD src0_sel:DWORD src1_sel:WORD_0
	v_cndmask_b32_e64 v12, 32, 24, s[2:3]
	v_cndmask_b32_e64 v13, v66, v67, s[2:3]
	v_cndmask_b32_e64 v6, v13, v12, s[0:1]
	v_lshl_add_u64 v[12:13], s[88:89], 0, v[6:7]
	global_load_dwordx2 v[16:17], v[12:13], off nt
	v_lshlrev_b32_sdwa v6, v65, sext(v15) dst_sel:DWORD dst_unused:UNUSED_PAD src0_sel:DWORD src1_sel:WORD_0
	v_lshlrev_b32_sdwa v12, v68, sext(v14) dst_sel:DWORD dst_unused:UNUSED_PAD src0_sel:DWORD src1_sel:WORD_0
	v_and_b32_e32 v6, 0xffffff80, v6
	v_and_b32_e32 v13, 0x60, v18
	v_or_b32_e32 v14, v12, v2
	v_or3_b32 v24, v6, v13, v5
	v_mul_i32_i24_e32 v22, 0xb00, v14
	v_ashrrev_i32_e32 v25, 31, v24
	v_mul_hi_i32_i24_e32 v21, 0x2c00, v14
	v_mul_i32_i24_e32 v20, 0x2c00, v14
	v_ashrrev_i32_e32 v23, 31, v22
	s_movk_i32 s30, 0x5000
	s_waitcnt vmcnt(0)
	v_lshl_add_u64 v[16:17], v[24:25], 2, v[16:17]
	v_lshl_add_u64 v[20:21], v[16:17], 0, v[20:21]
	v_lshl_add_u64 v[16:17], v[22:23], 2, v[16:17]
	v_add_co_u32_e32 v22, vcc, s30, v16
	s_mov_b32 s30, 0xb000
	s_nop 0
	v_addc_co_u32_e32 v23, vcc, 0, v17, vcc
	v_add_co_u32_e32 v24, vcc, s30, v16
	s_mov_b32 s30, 0x1b000
	s_nop 0
	v_addc_co_u32_e32 v25, vcc, 0, v17, vcc
	v_add_co_u32_e32 v26, vcc, s41, v16
	s_nop 1
	v_addc_co_u32_e32 v27, vcc, 0, v17, vcc
	v_add_co_u32_e32 v28, vcc, s42, v16
	s_nop 1
	v_addc_co_u32_e32 v29, vcc, 0, v17, vcc
	v_add_co_u32_e32 v76, vcc, s30, v16
	s_mov_b32 s30, 0x21000
	s_nop 0
	v_addc_co_u32_e32 v77, vcc, 0, v17, vcc
	v_add_co_u32_e32 v78, vcc, s30, v16
	s_mov_b32 s30, 0x31000
	s_nop 0
	v_addc_co_u32_e32 v79, vcc, 0, v17, vcc
	v_add_co_u32_e32 v80, vcc, s43, v16
	s_nop 1
	v_addc_co_u32_e32 v81, vcc, 0, v17, vcc
	v_add_co_u32_e32 v82, vcc, s44, v16
	global_load_dword v15, v[20:21], off nt
	global_load_dword v13, v[22:23], off offset:2048 nt
	global_load_dword v91, v[24:25], off nt
	global_load_dword v90, v[26:27], off offset:2048 nt
	global_load_dword v89, v[28:29], off nt
	global_load_dword v88, v[76:77], off offset:2048 nt
	global_load_dword v87, v[78:79], off nt
	global_load_dword v86, v[80:81], off offset:2048 nt
	v_addc_co_u32_e32 v83, vcc, 0, v17, vcc
	v_add_co_u32_e32 v92, vcc, s30, v16
	s_mov_b32 s30, 0x37000
	s_nop 0
	v_addc_co_u32_e32 v93, vcc, 0, v17, vcc
	v_add_co_u32_e32 v94, vcc, s30, v16
	s_mov_b32 s30, 0x42000
	s_nop 0
	v_addc_co_u32_e32 v95, vcc, 0, v17, vcc
	v_add_co_u32_e32 v96, vcc, s45, v16
	s_nop 1
	v_addc_co_u32_e32 v97, vcc, 0, v17, vcc
	v_add_co_u32_e32 v98, vcc, s30, v16
	s_mov_b32 s30, 0x47000
	s_nop 0
	v_addc_co_u32_e32 v99, vcc, 0, v17, vcc
	v_add_co_u32_e32 v100, vcc, s30, v16
	s_mov_b32 s30, 0x4d000
	s_nop 0
	v_addc_co_u32_e32 v101, vcc, 0, v17, vcc
	v_add_co_u32_e32 v102, vcc, s30, v16
	s_mov_b32 s30, 0x52000
	s_nop 0
	v_addc_co_u32_e32 v103, vcc, 0, v17, vcc
	v_add_co_u32_e32 v20, vcc, s30, v16
	s_mov_b32 s30, 0x58000
	s_nop 0
	v_addc_co_u32_e32 v21, vcc, 0, v17, vcc
	global_load_dword v85, v[82:83], off nt
	global_load_dword v84, v[92:93], off offset:2048 nt
	s_nop 0
	global_load_dword v83, v[94:95], off nt
	global_load_dword v82, v[96:97], off offset:2048 nt
	global_load_dword v81, v[98:99], off nt
	global_load_dword v80, v[100:101], off offset:2048 nt
	global_load_dword v78, v[102:103], off nt
	global_load_dword v76, v[20:21], off offset:2048 nt
	v_add_co_u32_e32 v20, vcc, s30, v16
	s_mov_b32 s30, 0x5d000
	s_nop 0
	v_addc_co_u32_e32 v21, vcc, 0, v17, vcc
	v_add_co_u32_e32 v22, vcc, s30, v16
	s_mov_b32 s30, 0x63000
	s_nop 0
	v_addc_co_u32_e32 v23, vcc, 0, v17, vcc
	v_add_co_u32_e32 v24, vcc, s30, v16
	s_mov_b32 s30, 0x68000
	s_nop 0
	v_addc_co_u32_e32 v25, vcc, 0, v17, vcc
	v_add_co_u32_e32 v26, vcc, s30, v16
	s_mov_b32 s30, 0x6e000
	s_nop 0
	v_addc_co_u32_e32 v27, vcc, 0, v17, vcc
	v_add_co_u32_e32 v92, vcc, s30, v16
	s_nop 1
	v_addc_co_u32_e32 v93, vcc, 0, v17, vcc
	v_add_co_u32_e32 v94, vcc, s46, v16
	s_nop 1
	v_addc_co_u32_e32 v95, vcc, 0, v17, vcc
	v_add_co_u32_e32 v96, vcc, s47, v16
	s_nop 1
	v_addc_co_u32_e32 v97, vcc, 0, v17, vcc
	v_add_co_u32_e32 v98, vcc, s48, v16
	s_nop 1
	v_addc_co_u32_e32 v99, vcc, 0, v17, vcc
	global_load_dword v79, v[20:21], off nt
	global_load_dword v77, v[22:23], off offset:2048 nt
	global_load_dword v75, v[24:25], off nt
	global_load_dword v29, v[26:27], off offset:2048 nt
	global_load_dword v28, v[92:93], off nt
	s_nop 0
	global_load_dword v27, v[94:95], off offset:2048 nt
	global_load_dword v25, v[96:97], off nt
	global_load_dword v23, v[98:99], off offset:2048 nt
	v_add_co_u32_e32 v20, vcc, s49, v16
	s_nop 1
	v_addc_co_u32_e32 v21, vcc, 0, v17, vcc
	v_add_co_u32_e32 v92, vcc, s50, v16
	s_nop 1
	v_addc_co_u32_e32 v93, vcc, 0, v17, vcc
	v_add_co_u32_e32 v94, vcc, s51, v16
	s_nop 1
	v_addc_co_u32_e32 v95, vcc, 0, v17, vcc
	v_add_co_u32_e32 v96, vcc, s52, v16
	s_nop 1
	v_addc_co_u32_e32 v97, vcc, 0, v17, vcc
	v_add_co_u32_e32 v98, vcc, s53, v16
	s_nop 1
	v_addc_co_u32_e32 v99, vcc, 0, v17, vcc
	v_add_co_u32_e32 v100, vcc, 0x9f000, v16
	s_nop 1
	v_addc_co_u32_e32 v101, vcc, 0, v17, vcc
	v_add_co_u32_e32 v102, vcc, 0xa5000, v16
	s_nop 1
	v_addc_co_u32_e32 v103, vcc, 0, v17, vcc
	v_add_co_u32_e32 v104, vcc, 0xaa000, v16
	v_cndmask_b32_e64 v16, v69, v70, s[2:3]
	s_nop 0
	v_addc_co_u32_e32 v105, vcc, 0, v17, vcc
	global_load_dword v26, v[20:21], off nt
	global_load_dword v24, v[92:93], off offset:2048 nt
	global_load_dword v22, v[94:95], off nt
	s_nop 0
	global_load_dword v21, v[96:97], off offset:2048 nt
	global_load_dword v20, v[98:99], off nt
	global_load_dword v19, v[100:101], off offset:2048 nt
	global_load_dword v17, v[102:103], off nt
	global_load_dword v6, v[104:105], off offset:2048 nt
	s_nor_b64 s[2:3], s[0:1], s[22:23]
	s_waitcnt vmcnt(31)
	v_mul_f32_e32 v92, v16, v15
	s_and_saveexec_b64 s[30:31], s[2:3]
	s_cbranch_execz .LBB0_98
	v_ashrrev_i32_e32 v15, 31, v14
	v_lshl_add_u64 v[14:15], v[14:15], 2, s[10:11]
	global_load_dword v14, v[14:15], off nt
	s_waitcnt vmcnt(0)
	v_mul_f32_e32 v92, v92, v14
;     ...
;     for (int i = 0; i < 32; ++i) { const int kk = 2 * i + (lane >> 5), k = k0 + kk; float v = wv[i] * cs; if (gain && k < gain_lim) v *= gain[k]; scr[kk * 33 + (lane & 31)] = v; }
.LBB0_98:
	s_or_b64 exec, exec, s[30:31]
	v_add_u32_e32 v14, v30, v31
	ds_write_b32 v14, v92
	s_waitcnt vmcnt(30)
	v_mul_f32_e32 v14, v16, v13
	v_ashrrev_i32_e32 v13, 31, v12
	s_and_saveexec_b64 s[30:31], s[2:3]
	s_cbranch_execz .LBB0_100
	v_lshl_add_u64 v[92:93], v[12:13], 0, v[2:3]
	v_lshl_add_u64 v[92:93], v[92:93], 2, s[10:11]
	global_load_dword v15, v[92:93], off offset:8 nt
	s_waitcnt vmcnt(0)
	v_mul_f32_e32 v14, v14, v15
.LBB0_100:
	s_or_b64 exec, exec, s[30:31]
	ds_write_b32 v73, v14
	s_waitcnt vmcnt(29)
	v_mul_f32_e32 v14, v16, v91
	s_and_saveexec_b64 s[30:31], s[2:3]
	s_cbranch_execz .LBB0_102
	v_lshl_add_u64 v[92:93], v[12:13], 0, v[2:3]
	v_lshl_add_u64 v[92:93], v[92:93], 2, s[10:11]
	global_load_dword v15, v[92:93], off offset:16 nt
	s_waitcnt vmcnt(0)
	v_mul_f32_e32 v14, v14, v15
.LBB0_102:
	s_or_b64 exec, exec, s[30:31]
	v_add_u32_e32 v15, v30, v32
	ds_write_b32 v15, v14
	s_waitcnt vmcnt(28)
	v_mul_f32_e32 v14, v16, v90
	s_and_saveexec_b64 s[30:31], s[2:3]
	s_cbranch_execz .LBB0_104
	v_lshl_add_u64 v[90:91], v[12:13], 0, v[2:3]
	v_lshl_add_u64 v[90:91], v[90:91], 2, s[10:11]
	global_load_dword v15, v[90:91], off offset:24 nt
	s_waitcnt vmcnt(0)
	v_mul_f32_e32 v14, v14, v15
.LBB0_104:
	s_or_b64 exec, exec, s[30:31]
	v_add_u32_e32 v15, v30, v33
	ds_write_b32 v15, v14
	s_waitcnt vmcnt(27)
	v_mul_f32_e32 v14, v16, v89
	s_and_saveexec_b64 s[30:31], s[2:3]
	s_cbranch_execz .LBB0_106
	v_lshl_add_u64 v[90:91], v[12:13], 0, v[2:3]
	v_lshl_add_u64 v[90:91], v[90:91], 2, s[10:11]
	global_load_dword v15, v[90:91], off offset:32 nt
	s_waitcnt vmcnt(0)
	v_mul_f32_e32 v14, v14, v15
.LBB0_106:
	s_or_b64 exec, exec, s[30:31]
	v_add_u32_e32 v15, v30, v34
	ds_write_b32 v15, v14
	s_waitcnt vmcnt(26)
	v_mul_f32_e32 v14, v16, v88
	s_and_saveexec_b64 s[30:31], s[2:3]
	s_cbranch_execz .LBB0_108
	v_lshl_add_u64 v[88:89], v[12:13], 0, v[2:3]
	v_lshl_add_u64 v[88:89], v[88:89], 2, s[10:11]
	global_load_dword v15, v[88:89], off offset:40 nt
	s_waitcnt vmcnt(0)
	v_mul_f32_e32 v14, v14, v15
.LBB0_108:
	s_or_b64 exec, exec, s[30:31]
	v_add_u32_e32 v15, v30, v35
	ds_write_b32 v15, v14
	s_waitcnt vmcnt(25)
	v_mul_f32_e32 v14, v16, v87
	s_and_saveexec_b64 s[30:31], s[2:3]
	s_cbranch_execz .LBB0_110
	v_lshl_add_u64 v[88:89], v[12:13], 0, v[2:3]
	v_lshl_add_u64 v[88:89], v[88:89], 2, s[10:11]
	global_load_dword v15, v[88:89], off offset:48 nt
	s_waitcnt vmcnt(0)
	v_mul_f32_e32 v14, v14, v15
.LBB0_110:
	s_or_b64 exec, exec, s[30:31]
	v_add_u32_e32 v15, v30, v36
	ds_write_b32 v15, v14
	s_waitcnt vmcnt(24)
	v_mul_f32_e32 v14, v16, v86
	s_and_saveexec_b64 s[30:31], s[2:3]
	s_cbranch_execz .LBB0_112
	v_lshl_add_u64 v[86:87], v[12:13], 0, v[2:3]
	v_lshl_add_u64 v[86:87], v[86:87], 2, s[10:11]
	global_load_dword v15, v[86:87], off offset:56 nt
	s_waitcnt vmcnt(0)
	v_mul_f32_e32 v14, v14, v15
.LBB0_112:
	s_or_b64 exec, exec, s[30:31]
	v_add_u32_e32 v15, v30, v37
	ds_write_b32 v15, v14
	s_waitcnt vmcnt(23)
	v_mul_f32_e32 v14, v16, v85
	s_and_saveexec_b64 s[30:31], s[2:3]
	s_cbranch_execz .LBB0_114
	v_lshl_add_u64 v[86:87], v[12:13], 0, v[2:3]
	v_lshl_add_u64 v[86:87], v[86:87], 2, s[10:11]
	global_load_dword v15, v[86:87], off offset:64 nt
	s_waitcnt vmcnt(0)
	v_mul_f32_e32 v14, v14, v15
.LBB0_114:
	s_or_b64 exec, exec, s[30:31]
	v_add_u32_e32 v15, v30, v38
	ds_write_b32 v15, v14
	s_waitcnt vmcnt(22)
	v_mul_f32_e32 v14, v16, v84
	s_and_saveexec_b64 s[30:31], s[2:3]
	s_cbranch_execz .LBB0_116
	v_lshl_add_u64 v[84:85], v[12:13], 0, v[2:3]
	v_lshl_add_u64 v[84:85], v[84:85], 2, s[10:11]
	global_load_dword v15, v[84:85], off offset:72 nt
	s_waitcnt vmcnt(0)
	v_mul_f32_e32 v14, v14, v15
.LBB0_116:
	s_or_b64 exec, exec, s[30:31]
	v_add_u32_e32 v15, v30, v39
	ds_write_b32 v15, v14
	s_waitcnt vmcnt(21)
	v_mul_f32_e32 v14, v16, v83
	s_and_saveexec_b64 s[30:31], s[2:3]
	s_cbranch_execz .LBB0_118
	v_lshl_add_u64 v[84:85], v[12:13], 0, v[2:3]
	v_lshl_add_u64 v[84:85], v[84:85], 2, s[10:11]
	global_load_dword v15, v[84:85], off offset:80 nt
	s_waitcnt vmcnt(0)
	v_mul_f32_e32 v14, v14, v15
.LBB0_118:
	s_or_b64 exec, exec, s[30:31]
	v_add_u32_e32 v15, v30, v40
	ds_write_b32 v15, v14
	s_waitcnt vmcnt(20)
	v_mul_f32_e32 v14, v16, v82
	s_and_saveexec_b64 s[30:31], s[2:3]
	s_cbranch_execz .LBB0_120
	v_lshl_add_u64 v[82:83], v[12:13], 0, v[2:3]
	v_lshl_add_u64 v[82:83], v[82:83], 2, s[10:11]
	global_load_dword v15, v[82:83], off offset:88 nt
	s_waitcnt vmcnt(0)
	v_mul_f32_e32 v14, v14, v15
.LBB0_120:
	s_or_b64 exec, exec, s[30:31]
	v_add_u32_e32 v15, v30, v41
	ds_write_b32 v15, v14
	s_waitcnt vmcnt(19)
	v_mul_f32_e32 v14, v16, v81
	s_and_saveexec_b64 s[30:31], s[2:3]
	s_cbranch_execz .LBB0_122
	v_lshl_add_u64 v[82:83], v[12:13], 0, v[2:3]
	v_lshl_add_u64 v[82:83], v[82:83], 2, s[10:11]
	global_load_dword v15, v[82:83], off offset:96 nt
	s_waitcnt vmcnt(0)
	v_mul_f32_e32 v14, v14, v15
.LBB0_122:
	s_or_b64 exec, exec, s[30:31]
	v_add_u32_e32 v15, v30, v42
	ds_write_b32 v15, v14
	s_waitcnt vmcnt(18)
	v_mul_f32_e32 v14, v16, v80
	s_and_saveexec_b64 s[30:31], s[2:3]
	s_cbranch_execz .LBB0_124
	v_lshl_add_u64 v[80:81], v[12:13], 0, v[2:3]
	v_lshl_add_u64 v[80:81], v[80:81], 2, s[10:11]
	global_load_dword v15, v[80:81], off offset:104 nt
	s_waitcnt vmcnt(0)
	v_mul_f32_e32 v14, v14, v15
.LBB0_124:
	s_or_b64 exec, exec, s[30:31]
	v_add_u32_e32 v15, v30, v43
	ds_write_b32 v15, v14
	s_waitcnt vmcnt(17)
	v_mul_f32_e32 v14, v16, v78
	s_and_saveexec_b64 s[30:31], s[2:3]
	s_cbranch_execz .LBB0_126
	v_lshl_add_u64 v[80:81], v[12:13], 0, v[2:3]
	v_lshl_add_u64 v[80:81], v[80:81], 2, s[10:11]
	global_load_dword v15, v[80:81], off offset:112 nt
	s_waitcnt vmcnt(0)
	v_mul_f32_e32 v14, v14, v15
;     ...
;     for (int i = 0; i < 32; ++i) { const int kk = 2 * i + (lane >> 5), k = k0 + kk; float v = wv[i] * cs; if (gain && k < gain_lim) v *= gain[k]; scr[kk * 33 + (lane & 31)] = v; }
.LBB0_126:
	s_or_b64 exec, exec, s[30:31]
	v_add_u32_e32 v15, v30, v44
	ds_write_b32 v15, v14
	s_waitcnt vmcnt(16)
	v_mul_f32_e32 v14, v16, v76
	s_and_saveexec_b64 s[30:31], s[2:3]
	s_cbranch_execz .LBB0_128
	v_lshl_add_u64 v[80:81], v[12:13], 0, v[2:3]
	v_lshl_add_u64 v[80:81], v[80:81], 2, s[10:11]
	global_load_dword v15, v[80:81], off offset:120 nt
	s_waitcnt vmcnt(0)
	v_mul_f32_e32 v14, v14, v15
.LBB0_128:
	s_or_b64 exec, exec, s[30:31]
	v_add_u32_e32 v15, v30, v45
	ds_write_b32 v15, v14
	s_waitcnt vmcnt(15)
	v_mul_f32_e32 v14, v16, v79
	s_and_saveexec_b64 s[30:31], s[2:3]
	s_cbranch_execz .LBB0_130
	v_lshl_add_u64 v[78:79], v[12:13], 0, v[2:3]
	v_lshl_add_u64 v[78:79], v[78:79], 2, s[10:11]
	global_load_dword v15, v[78:79], off offset:128 nt
	s_waitcnt vmcnt(0)
	v_mul_f32_e32 v14, v14, v15
.LBB0_130:
	s_or_b64 exec, exec, s[30:31]
	v_add_u32_e32 v15, v30, v46
	ds_write_b32 v15, v14
	s_waitcnt vmcnt(14)
	v_mul_f32_e32 v14, v16, v77
	s_and_saveexec_b64 s[30:31], s[2:3]
	s_cbranch_execz .LBB0_132
	v_lshl_add_u64 v[76:77], v[12:13], 0, v[2:3]
	v_lshl_add_u64 v[76:77], v[76:77], 2, s[10:11]
	global_load_dword v15, v[76:77], off offset:136 nt
	s_waitcnt vmcnt(0)
	v_mul_f32_e32 v14, v14, v15
.LBB0_132:
	s_or_b64 exec, exec, s[30:31]
	v_add_u32_e32 v15, v30, v47
	ds_write_b32 v15, v14
	s_waitcnt vmcnt(13)
	v_mul_f32_e32 v14, v16, v75
	s_and_saveexec_b64 s[30:31], s[2:3]
	s_cbranch_execz .LBB0_134
	v_lshl_add_u64 v[76:77], v[12:13], 0, v[2:3]
	v_lshl_add_u64 v[76:77], v[76:77], 2, s[10:11]
	global_load_dword v15, v[76:77], off offset:144 nt
	s_waitcnt vmcnt(0)
	v_mul_f32_e32 v14, v14, v15
.LBB0_134:
	s_or_b64 exec, exec, s[30:31]
	v_add_u32_e32 v15, v30, v48
	ds_write_b32 v15, v14
	s_waitcnt vmcnt(12)
	v_mul_f32_e32 v14, v16, v29
	s_and_saveexec_b64 s[30:31], s[2:3]
	s_cbranch_execz .LBB0_136
	v_lshl_add_u64 v[76:77], v[12:13], 0, v[2:3]
	v_lshl_add_u64 v[76:77], v[76:77], 2, s[10:11]
	global_load_dword v15, v[76:77], off offset:152 nt
	s_waitcnt vmcnt(0)
	v_mul_f32_e32 v14, v14, v15
.LBB0_136:
	s_or_b64 exec, exec, s[30:31]
	v_add_u32_e32 v15, v30, v49
	ds_write_b32 v15, v14
	s_waitcnt vmcnt(11)
	v_mul_f32_e32 v14, v16, v28
	s_and_saveexec_b64 s[30:31], s[2:3]
	s_cbranch_execz .LBB0_138
	v_lshl_add_u64 v[28:29], v[12:13], 0, v[2:3]
	v_lshl_add_u64 v[28:29], v[28:29], 2, s[10:11]
	global_load_dword v15, v[28:29], off offset:160 nt
	s_waitcnt vmcnt(0)
	v_mul_f32_e32 v14, v14, v15
.LBB0_138:
	s_or_b64 exec, exec, s[30:31]
	v_add_u32_e32 v15, v30, v50
	ds_write_b32 v15, v14
	s_waitcnt vmcnt(10)
	v_mul_f32_e32 v14, v16, v27
	s_and_saveexec_b64 s[30:31], s[2:3]
	s_cbranch_execz .LBB0_140
	v_lshl_add_u64 v[28:29], v[12:13], 0, v[2:3]
	v_lshl_add_u64 v[28:29], v[28:29], 2, s[10:11]
	global_load_dword v15, v[28:29], off offset:168 nt
	s_waitcnt vmcnt(0)
	v_mul_f32_e32 v14, v14, v15
.LBB0_140:
	s_or_b64 exec, exec, s[30:31]
	v_add_u32_e32 v15, v30, v51
	ds_write_b32 v15, v14
	s_waitcnt vmcnt(9)
	v_mul_f32_e32 v15, v16, v25
	s_and_saveexec_b64 s[30:31], s[2:3]
	s_cbranch_execz .LBB0_142
	v_lshl_add_u64 v[28:29], v[12:13], 0, v[2:3]
	v_lshl_add_u64 v[28:29], v[28:29], 2, s[10:11]
	global_load_dword v14, v[28:29], off offset:176 nt
	s_waitcnt vmcnt(0)
	v_mul_f32_e32 v15, v15, v14
.LBB0_142:
	s_or_b64 exec, exec, s[30:31]
	v_add_u32_e32 v14, v30, v52
	ds_write_b32 v14, v15
	s_waitcnt vmcnt(8)
	v_mul_f32_e32 v15, v16, v23
	s_and_saveexec_b64 s[30:31], s[2:3]
	s_cbranch_execz .LBB0_144
	v_lshl_add_u64 v[28:29], v[12:13], 0, v[2:3]
	v_lshl_add_u64 v[28:29], v[28:29], 2, s[10:11]
	global_load_dword v23, v[28:29], off offset:184 nt
	s_waitcnt vmcnt(0)
	v_mul_f32_e32 v15, v15, v23
.LBB0_144:
	s_or_b64 exec, exec, s[30:31]
	ds_write_b32 v14, v15 offset:264
	s_waitcnt vmcnt(7)
	v_mul_f32_e32 v15, v16, v26
	s_and_saveexec_b64 s[30:31], s[2:3]
	s_cbranch_execz .LBB0_146
	v_lshl_add_u64 v[26:27], v[12:13], 0, v[2:3]
	v_lshl_add_u64 v[26:27], v[26:27], 2, s[10:11]
	global_load_dword v23, v[26:27], off offset:192 nt
	s_waitcnt vmcnt(0)
	v_mul_f32_e32 v15, v15, v23
.LBB0_146:
	s_or_b64 exec, exec, s[30:31]
	ds_write_b32 v14, v15 offset:528
	s_waitcnt vmcnt(6)
	v_mul_f32_e32 v15, v16, v24
	s_and_saveexec_b64 s[30:31], s[2:3]
	s_cbranch_execz .LBB0_148
	v_lshl_add_u64 v[24:25], v[12:13], 0, v[2:3]
	v_lshl_add_u64 v[24:25], v[24:25], 2, s[10:11]
	global_load_dword v23, v[24:25], off offset:200 nt
	s_waitcnt vmcnt(0)
	v_mul_f32_e32 v15, v15, v23
.LBB0_148:
	s_or_b64 exec, exec, s[30:31]
	ds_write_b32 v14, v15 offset:792
	s_waitcnt vmcnt(5)
	v_mul_f32_e32 v15, v16, v22
	s_and_saveexec_b64 s[30:31], s[2:3]
	s_cbranch_execz .LBB0_150
	v_lshl_add_u64 v[22:23], v[12:13], 0, v[2:3]
	v_lshl_add_u64 v[22:23], v[22:23], 2, s[10:11]
	global_load_dword v22, v[22:23], off offset:208 nt
	s_waitcnt vmcnt(0)
	v_mul_f32_e32 v15, v15, v22
.LBB0_150:
	s_or_b64 exec, exec, s[30:31]
	ds_write_b32 v14, v15 offset:1056
	s_waitcnt vmcnt(4)
	v_mul_f32_e32 v15, v16, v21
	s_and_saveexec_b64 s[30:31], s[2:3]
	s_cbranch_execz .LBB0_152
	v_lshl_add_u64 v[22:23], v[12:13], 0, v[2:3]
	v_lshl_add_u64 v[22:23], v[22:23], 2, s[10:11]
	global_load_dword v21, v[22:23], off offset:216 nt
	s_waitcnt vmcnt(0)
	v_mul_f32_e32 v15, v15, v21
.LBB0_152:
	s_or_b64 exec, exec, s[30:31]
	ds_write_b32 v14, v15 offset:1320
	s_waitcnt vmcnt(3)
	v_mul_f32_e32 v15, v16, v20
	s_and_saveexec_b64 s[30:31], s[2:3]
	s_cbranch_execz .LBB0_154
	v_lshl_add_u64 v[20:21], v[12:13], 0, v[2:3]
	v_lshl_add_u64 v[20:21], v[20:21], 2, s[10:11]
	global_load_dword v20, v[20:21], off offset:224 nt
	s_waitcnt vmcnt(0)
	v_mul_f32_e32 v15, v15, v20
.LBB0_154:
	s_or_b64 exec, exec, s[30:31]
	ds_write_b32 v14, v15 offset:1584
	s_waitcnt vmcnt(2)
	v_mul_f32_e32 v15, v16, v19
	s_and_saveexec_b64 s[30:31], s[2:3]
	s_cbranch_execz .LBB0_156
	v_lshl_add_u64 v[20:21], v[12:13], 0, v[2:3]
	v_lshl_add_u64 v[20:21], v[20:21], 2, s[10:11]
	global_load_dword v19, v[20:21], off offset:232 nt
	s_waitcnt vmcnt(0)
	v_mul_f32_e32 v15, v15, v19
.LBB0_156:
	s_or_b64 exec, exec, s[30:31]
	ds_write_b32 v14, v15 offset:1848
	s_waitcnt vmcnt(1)
	v_mul_f32_e32 v15, v16, v17
	s_and_saveexec_b64 s[30:31], s[2:3]
	s_cbranch_execz .LBB0_158
	v_lshl_add_u64 v[20:21], v[12:13], 0, v[2:3]
	v_lshl_add_u64 v[20:21], v[20:21], 2, s[10:11]
	global_load_dword v17, v[20:21], off offset:240 nt
	s_waitcnt vmcnt(0)
	v_mul_f32_e32 v15, v15, v17
.LBB0_158:
	s_or_b64 exec, exec, s[30:31]
	ds_write_b32 v14, v15 offset:2112
	s_waitcnt vmcnt(0)
	v_mul_f32_e32 v15, v16, v6
	s_and_saveexec_b64 s[30:31], s[2:3]
	s_xor_b64 s[2:3], exec, s[30:31]
	s_cbranch_execz .LBB0_24
	v_lshl_add_u64 v[16:17], v[12:13], 0, v[2:3]
	v_lshl_add_u64 v[16:17], v[16:17], 2, s[10:11]
	global_load_dword v6, v[16:17], off offset:248 nt
	s_waitcnt vmcnt(0)
	v_mul_f32_e32 v15, v15, v6
	s_branch .LBB0_24

; __device__ __forceinline__ unsigned pk2(float lo, float hi) { return f2bf(lo) | (f2bf(hi) << 16); }
; __device__ __forceinline__ void p0_prologue(const Params& p, LAS unsigned char* lds, int G) {
;     ...
;     for (int rb = gw * 4; rb < T; rb += NGW * 4) {
;         f32x4 v[4][4]; float s[4];
; #pragma unroll
;         for (int q = 0; q < 4; ++q) { const int row = rb + q; const float* xrow = row < TP ? p.in[0] + (size_t)row * D : p.in[1] + (size_t)(row - TP) * D; const f32x4* xr = (const f32x4*)xrow + lane;
; #pragma unroll
;             for (int j = 0; j < 4; ++j) v[q][j] = xr[64 * j]; }
; #pragma unroll
;         for (int q = 0; q < 4; ++q) { float a = 0.f;
; #pragma unroll
;             for (int j = 0; j < 4; ++j) a += (v[q][j][0] * v[q][j][0] + v[q][j][1] * v[q][j][1]) + (v[q][j][2] * v[q][j][2] + v[q][j][3] * v[q][j][3]);
;             s[q] = a; }
; #pragma unroll
;         for (int q = 0; q < 4; ++q) { const float rstd = __builtin_amdgcn_rsqf(wave_sum(s[q]) * (1.f / D) + EPS);
;             u32x2* o8 = (u32x2*)(XN + (size_t)(rb + q) * D) + lane;
; #pragma unroll
;             for (int j = 0; j < 4; ++j) { const f32x4 g = gp[64 * j]; u32x2 w; w.x = pk2(v[q][j][0] * rstd * g[0], v[q][j][1] * rstd * g[1]); w.y = pk2(v[q][j][2] * rstd * g[2], v[q][j][3] * rstd * g[3]); o8[64 * j] = w; } }
.LBB0_171:
	s_or_b64 exec, exec, s[0:1]
	v_mov_b32_e32 v92, v112
	v_mov_b32_e32 v93, v113
	v_mov_b32_e32 v94, v114
	v_mov_b32_e32 v95, v115
	s_waitcnt vmcnt(11)
	v_pk_mul_f32 v[14:15], v[62:63], v[62:63]
	v_pk_mul_f32 v[20:21], v[60:61], v[60:61]
	s_waitcnt vmcnt(10)
	v_pk_mul_f32 v[22:23], v[58:59], v[58:59]
	v_pk_mul_f32 v[24:25], v[56:57], v[56:57]
	v_pk_mov_b32 v[34:35], v[20:21], v[14:15] op_sel:[1,0]
	v_mov_b32_e32 v21, v15
	v_pk_mov_b32 v[14:15], v[24:25], v[22:23] op_sel:[1,0]
	v_mov_b32_e32 v25, v23
	s_waitcnt vmcnt(8)
	v_mul_f32_e32 v33, v48, v48
	v_mul_f32_e32 v26, v53, v53
	v_mul_f32_e32 v32, v55, v55
	v_pk_add_f32 v[20:21], v[34:35], v[20:21]
	v_pk_add_f32 v[14:15], v[14:15], v[24:25]
	v_mul_f32_e32 v91, v49, v49
	v_mul_f32_e32 v96, v50, v50
	v_mul_f32_e32 v97, v51, v51
	v_pk_fma_f32 v[22:23], v[52:53], v[52:53], v[26:27] op_sel_hi:[1,1,0]
	v_pk_fma_f32 v[26:27], v[54:55], v[54:55], v[32:33] op_sel_hi:[1,1,0]
	v_pk_add_f32 v[20:21], v[20:21], v[20:21] op_sel:[0,1] op_sel_hi:[1,0]
	v_pk_add_f32 v[14:15], v[14:15], v[14:15] op_sel:[0,1] op_sel_hi:[1,0]
	v_mov_b32_e32 v23, v96
	v_mov_b32_e32 v27, v97
	v_mov_b32_e32 v21, v33
	v_mov_b32_e32 v15, v91
	v_pk_add_f32 v[22:23], v[22:23], v[26:27]
	v_pk_add_f32 v[14:15], v[20:21], v[14:15]
	v_lshl_add_u64 v[96:97], v[12:13], 0, v[64:65]
	v_pk_add_f32 v[14:15], v[14:15], v[22:23]
	v_mov_b32_e32 v99, v62
	v_add_f32_e32 v14, v14, v15
	ds_bpermute_b32 v15, v80, v14
	v_mov_b32_e32 v62, v61
	v_mov_b32_e32 v98, v60
	v_add_co_u32_e32 v100, vcc, s20, v76
	s_waitcnt lgkmcnt(0)
	v_add_f32_e32 v14, v14, v15
	ds_bpermute_b32 v15, v81, v14
	v_addc_co_u32_e32 v101, vcc, -1, v77, vcc
	v_add_u32_e32 v66, s6, v66
	v_cmp_lt_i32_e32 vcc, s21, v66
	s_waitcnt lgkmcnt(0)
	v_add_f32_e32 v14, v14, v15
	ds_bpermute_b32 v15, v82, v14
	v_lshl_add_u64 v[72:73], v[72:73], 0, s[6:7]
	v_lshl_add_u64 v[74:75], v[74:75], 0, s[8:9]
	s_or_b64 s[16:17], vcc, s[16:17]
	s_waitcnt lgkmcnt(0)
	v_add_f32_e32 v14, v14, v15
	ds_bpermute_b32 v15, v83, v14
	s_waitcnt lgkmcnt(0)
	v_add_f32_e32 v14, v14, v15
	ds_bpermute_b32 v15, v84, v14
	s_waitcnt lgkmcnt(0)
	v_add_f32_e32 v12, v14, v15
	ds_bpermute_b32 v13, v85, v12
	s_waitcnt lgkmcnt(0)
	v_add_f32_e32 v12, v12, v13
	v_fmamk_f32 v12, v12, 0x3a800000, v89
	v_rsq_f32_e32 v102, v12
	global_load_dwordx4 v[32:35], v[96:97], off nt
	global_load_dwordx4 v[24:27], v[96:97], off offset:1024 nt
	global_load_dwordx4 v[20:23], v[96:97], off offset:2048 nt
	global_load_dwordx4 v[12:15], v[96:97], off offset:3072 nt
	v_pk_mul_f32 v[62:63], v[62:63], v[102:103] op_sel_hi:[1,0]
	v_pk_mul_f32 v[60:61], v[98:99], v[102:103] op_sel_hi:[1,0]
	s_waitcnt vmcnt(4)
	v_mov_b32_e32 v97, v94
	v_mov_b32_e32 v94, v93
	v_mov_b32_e32 v96, v92
	v_pk_mul_f32 v[62:63], v[94:95], v[62:63]
	v_pk_mul_f32 v[60:61], v[96:97], v[60:61]
	v_and_b32_sdwa v93, v63, v90 dst_sel:DWORD dst_unused:UNUSED_PAD src0_sel:WORD_1 src1_sel:DWORD
	v_and_b32_sdwa v94, v62, v90 dst_sel:DWORD dst_unused:UNUSED_PAD src0_sel:WORD_1 src1_sel:DWORD
	v_and_b32_sdwa v91, v61, v90 dst_sel:DWORD dst_unused:UNUSED_PAD src0_sel:WORD_1 src1_sel:DWORD
	v_and_b32_sdwa v92, v60, v90 dst_sel:DWORD dst_unused:UNUSED_PAD src0_sel:WORD_1 src1_sel:DWORD
	v_add3_u32 v63, v63, v93, s19
	v_add3_u32 v62, v62, v94, s19
	v_add3_u32 v60, v60, v92, s19
	v_add3_u32 v61, v61, v91, s19
	v_and_b32_e32 v63, 0xffff0000, v63
	v_and_b32_e32 v62, 0xffff0000, v62
	v_or_b32_sdwa v61, v63, v61 dst_sel:DWORD dst_unused:UNUSED_PAD src0_sel:DWORD src1_sel:WORD_1
	v_or_b32_sdwa v60, v62, v60 dst_sel:DWORD dst_unused:UNUSED_PAD src0_sel:DWORD src1_sel:WORD_1
	global_store_dwordx2 v[100:101], v[60:61], off offset:-1536
	v_mov_b32_e32 v60, v116
	v_mov_b32_e32 v61, v117
	v_mov_b32_e32 v62, v118
	v_mov_b32_e32 v63, v119
	v_mov_b32_e32 v92, v56
	v_mov_b32_e32 v93, v58
	v_mov_b32_e32 v58, v57
	v_pk_mul_f32 v[56:57], v[92:93], v[102:103] op_sel_hi:[1,0]
	v_pk_mul_f32 v[58:59], v[58:59], v[102:103] op_sel_hi:[1,0]
	v_mul_f32_e32 v91, v29, v29
	v_mul_f32_e32 v94, v30, v30
	v_mul_f32_e32 v95, v31, v31
	s_waitcnt vmcnt(1)
	v_mov_b32_e32 v93, v62
	v_mov_b32_e32 v62, v61
	v_mov_b32_e32 v92, v60
	v_pk_mul_f32 v[58:59], v[62:63], v[58:59]
	v_pk_mul_f32 v[56:57], v[92:93], v[56:57]
	v_and_b32_sdwa v62, v59, v90 dst_sel:DWORD dst_unused:UNUSED_PAD src0_sel:WORD_1 src1_sel:DWORD
	v_and_b32_sdwa v63, v58, v90 dst_sel:DWORD dst_unused:UNUSED_PAD src0_sel:WORD_1 src1_sel:DWORD
	v_and_b32_sdwa v60, v57, v90 dst_sel:DWORD dst_unused:UNUSED_PAD src0_sel:WORD_1 src1_sel:DWORD
	v_and_b32_sdwa v61, v56, v90 dst_sel:DWORD dst_unused:UNUSED_PAD src0_sel:WORD_1 src1_sel:DWORD
	v_add3_u32 v59, v59, v62, s19
	v_add3_u32 v58, v58, v63, s19
	v_add3_u32 v56, v56, v61, s19
	v_add3_u32 v57, v57, v60, s19
	v_and_b32_e32 v59, 0xffff0000, v59
	v_and_b32_e32 v58, 0xffff0000, v58
	v_or_b32_sdwa v57, v59, v57 dst_sel:DWORD dst_unused:UNUSED_PAD src0_sel:DWORD src1_sel:WORD_1
	v_or_b32_sdwa v56, v58, v56 dst_sel:DWORD dst_unused:UNUSED_PAD src0_sel:DWORD src1_sel:WORD_1
	global_store_dwordx2 v[100:101], v[56:57], off offset:-1024
	v_mov_b32_e32 v56, v120
	v_mov_b32_e32 v57, v121
	v_mov_b32_e32 v58, v122
	v_mov_b32_e32 v59, v123
	v_mov_b32_e32 v60, v52
	v_mov_b32_e32 v61, v54
	v_mov_b32_e32 v54, v53
	v_pk_mul_f32 v[52:53], v[60:61], v[102:103] op_sel_hi:[1,0]
	v_pk_mul_f32 v[54:55], v[54:55], v[102:103] op_sel_hi:[1,0]
	v_mul_f32_e32 v63, v28, v28
	v_mul_f32_e32 v62, v39, v39
	v_mov_b32_e32 v61, v58
	v_mov_b32_e32 v58, v57
	v_mov_b32_e32 v60, v56
	v_pk_mul_f32 v[54:55], v[58:59], v[54:55]
	v_pk_mul_f32 v[52:53], v[60:61], v[52:53]
	v_and_b32_sdwa v58, v55, v90 dst_sel:DWORD dst_unused:UNUSED_PAD src0_sel:WORD_1 src1_sel:DWORD
; __device__ __forceinline__ unsigned pk2(float lo, float hi) { return f2bf(lo) | (f2bf(hi) << 16); }
; __device__ __forceinline__ void p0_prologue(const Params& p, LAS unsigned char* lds, int G) {
;     ...
;         for (int q = 0; q < 4; ++q) { float a = 0.f;
; #pragma unroll
;             for (int j = 0; j < 4; ++j) a += (v[q][j][0] * v[q][j][0] + v[q][j][1] * v[q][j][1]) + (v[q][j][2] * v[q][j][2] + v[q][j][3] * v[q][j][3]);
;             s[q] = a; }
; #pragma unroll
;         for (int q = 0; q < 4; ++q) { const float rstd = __builtin_amdgcn_rsqf(wave_sum(s[q]) * (1.f / D) + EPS);
;             u32x2* o8 = (u32x2*)(XN + (size_t)(rb + q) * D) + lane;
; #pragma unroll
;             for (int j = 0; j < 4; ++j) { const f32x4 g = gp[64 * j]; u32x2 w; w.x = pk2(v[q][j][0] * rstd * g[0], v[q][j][1] * rstd * g[1]); w.y = pk2(v[q][j][2] * rstd * g[2], v[q][j][3] * rstd * g[3]); o8[64 * j] = w; } }
	v_and_b32_sdwa v59, v54, v90 dst_sel:DWORD dst_unused:UNUSED_PAD src0_sel:WORD_1 src1_sel:DWORD
	v_and_b32_sdwa v56, v53, v90 dst_sel:DWORD dst_unused:UNUSED_PAD src0_sel:WORD_1 src1_sel:DWORD
	v_and_b32_sdwa v57, v52, v90 dst_sel:DWORD dst_unused:UNUSED_PAD src0_sel:WORD_1 src1_sel:DWORD
	v_add3_u32 v55, v55, v58, s19
	v_add3_u32 v54, v54, v59, s19
	v_add3_u32 v52, v52, v57, s19
	v_add3_u32 v53, v53, v56, s19
	v_and_b32_e32 v55, 0xffff0000, v55
	v_and_b32_e32 v54, 0xffff0000, v54
	v_or_b32_sdwa v53, v55, v53 dst_sel:DWORD dst_unused:UNUSED_PAD src0_sel:DWORD src1_sel:WORD_1
	v_or_b32_sdwa v52, v54, v52 dst_sel:DWORD dst_unused:UNUSED_PAD src0_sel:DWORD src1_sel:WORD_1
	global_store_dwordx2 v[100:101], v[52:53], off offset:-512
	v_mov_b32_e32 v52, v124
	v_mov_b32_e32 v53, v125
	v_mov_b32_e32 v54, v126
	v_mov_b32_e32 v55, v127
	v_mov_b32_e32 v56, v48
	v_mov_b32_e32 v57, v50
	v_mov_b32_e32 v50, v49
	v_pk_mul_f32 v[48:49], v[56:57], v[102:103] op_sel_hi:[1,0]
	v_pk_mul_f32 v[50:51], v[50:51], v[102:103] op_sel_hi:[1,0]
	v_pk_mul_f32 v[58:59], v[40:41], v[40:41]
	v_mul_f32_e32 v60, v37, v37
	v_mov_b32_e32 v57, v54
	v_mov_b32_e32 v54, v53
	v_mov_b32_e32 v56, v52
	v_pk_mul_f32 v[50:51], v[50:51], v[54:55]
	v_pk_mul_f32 v[48:49], v[48:49], v[56:57]
	v_and_b32_sdwa v54, v51, v90 dst_sel:DWORD dst_unused:UNUSED_PAD src0_sel:WORD_1 src1_sel:DWORD
	v_and_b32_sdwa v55, v50, v90 dst_sel:DWORD dst_unused:UNUSED_PAD src0_sel:WORD_1 src1_sel:DWORD
	v_and_b32_sdwa v52, v49, v90 dst_sel:DWORD dst_unused:UNUSED_PAD src0_sel:WORD_1 src1_sel:DWORD
	v_and_b32_sdwa v53, v48, v90 dst_sel:DWORD dst_unused:UNUSED_PAD src0_sel:WORD_1 src1_sel:DWORD
	v_add3_u32 v51, v51, v54, s19
	v_add3_u32 v50, v50, v55, s19
	v_add3_u32 v48, v48, v53, s19
	v_add3_u32 v49, v49, v52, s19
	v_and_b32_e32 v51, 0xffff0000, v51
	v_and_b32_e32 v50, 0xffff0000, v50
	v_or_b32_sdwa v49, v51, v49 dst_sel:DWORD dst_unused:UNUSED_PAD src0_sel:DWORD src1_sel:WORD_1
	v_or_b32_sdwa v48, v50, v48 dst_sel:DWORD dst_unused:UNUSED_PAD src0_sel:DWORD src1_sel:WORD_1
	global_store_dwordx2 v[76:77], v[48:49], off offset:-4096
	v_mov_b32_e32 v48, v112
	v_mov_b32_e32 v49, v113
	v_mov_b32_e32 v50, v114
	v_mov_b32_e32 v51, v115
	v_pk_mul_f32 v[52:53], v[46:47], v[46:47]
	v_pk_mul_f32 v[54:55], v[44:45], v[44:45]
	v_pk_mul_f32 v[56:57], v[42:43], v[42:43]
	v_pk_mov_b32 v[92:93], v[54:55], v[52:53] op_sel:[1,0]
	v_mov_b32_e32 v55, v53
	v_pk_mov_b32 v[52:53], v[58:59], v[56:57] op_sel:[1,0]
	v_mov_b32_e32 v59, v57
	v_pk_add_f32 v[54:55], v[92:93], v[54:55]
	v_pk_add_f32 v[52:53], v[52:53], v[58:59]
	v_pk_fma_f32 v[56:57], v[36:37], v[36:37], v[60:61] op_sel_hi:[1,1,0]
	v_pk_fma_f32 v[60:61], v[38:39], v[38:39], v[62:63] op_sel_hi:[1,1,0]
	v_pk_add_f32 v[54:55], v[54:55], v[54:55] op_sel:[0,1] op_sel_hi:[1,0]
	v_pk_add_f32 v[52:53], v[52:53], v[52:53] op_sel:[0,1] op_sel_hi:[1,0]
	v_mov_b32_e32 v57, v94
	v_mov_b32_e32 v61, v95
	v_mov_b32_e32 v55, v63
	v_mov_b32_e32 v53, v91
	v_pk_add_f32 v[56:57], v[56:57], v[60:61]
	v_pk_add_f32 v[52:53], v[54:55], v[52:53]
	v_mov_b32_e32 v54, v44
	v_pk_add_f32 v[52:53], v[52:53], v[56:57]
	v_mov_b32_e32 v55, v46
	v_add_f32_e32 v52, v52, v53
	ds_bpermute_b32 v53, v80, v52
	v_mov_b32_e32 v46, v45
	s_waitcnt lgkmcnt(0)
	v_add_f32_e32 v52, v52, v53
	ds_bpermute_b32 v53, v81, v52
	s_waitcnt lgkmcnt(0)
	v_add_f32_e32 v52, v52, v53
	ds_bpermute_b32 v53, v82, v52
	s_waitcnt lgkmcnt(0)
	v_add_f32_e32 v52, v52, v53
	ds_bpermute_b32 v53, v83, v52
	s_waitcnt lgkmcnt(0)
	v_add_f32_e32 v52, v52, v53
	ds_bpermute_b32 v53, v84, v52
	s_waitcnt lgkmcnt(0)
	v_add_f32_e32 v52, v52, v53
	ds_bpermute_b32 v53, v85, v52
	s_waitcnt lgkmcnt(0)
	v_add_f32_e32 v52, v52, v53
	v_fmamk_f32 v52, v52, 0x3a800000, v89
	v_rsq_f32_e32 v52, v52
	s_nop 0
	v_pk_mul_f32 v[44:45], v[54:55], v[52:53] op_sel_hi:[1,0]
	v_pk_mul_f32 v[46:47], v[46:47], v[52:53] op_sel_hi:[1,0]
	v_mov_b32_e32 v55, v50
	v_mov_b32_e32 v50, v49
	v_mov_b32_e32 v54, v48
	v_pk_mul_f32 v[46:47], v[50:51], v[46:47]
	v_pk_mul_f32 v[44:45], v[54:55], v[44:45]
	v_and_b32_sdwa v50, v47, v90 dst_sel:DWORD dst_unused:UNUSED_PAD src0_sel:WORD_1 src1_sel:DWORD
	v_and_b32_sdwa v51, v46, v90 dst_sel:DWORD dst_unused:UNUSED_PAD src0_sel:WORD_1 src1_sel:DWORD
	v_and_b32_sdwa v48, v45, v90 dst_sel:DWORD dst_unused:UNUSED_PAD src0_sel:WORD_1 src1_sel:DWORD
	v_and_b32_sdwa v49, v44, v90 dst_sel:DWORD dst_unused:UNUSED_PAD src0_sel:WORD_1 src1_sel:DWORD
	v_add3_u32 v47, v47, v50, s19
	v_add3_u32 v46, v46, v51, s19
	v_add3_u32 v44, v44, v49, s19
	v_add3_u32 v45, v45, v48, s19
	v_and_b32_e32 v47, 0xffff0000, v47
	v_and_b32_e32 v46, 0xffff0000, v46
	v_or_b32_sdwa v45, v47, v45 dst_sel:DWORD dst_unused:UNUSED_PAD src0_sel:DWORD src1_sel:WORD_1
	v_or_b32_sdwa v44, v46, v44 dst_sel:DWORD dst_unused:UNUSED_PAD src0_sel:DWORD src1_sel:WORD_1
	global_store_dwordx2 v[76:77], v[44:45], off offset:-3584
	v_mov_b32_e32 v44, v116
	v_mov_b32_e32 v45, v117
	v_mov_b32_e32 v46, v118
	v_mov_b32_e32 v47, v119
	v_mov_b32_e32 v48, v40
	v_mov_b32_e32 v49, v42
	v_mov_b32_e32 v42, v41
	v_pk_mul_f32 v[40:41], v[48:49], v[52:53] op_sel_hi:[1,0]
	v_pk_mul_f32 v[42:43], v[42:43], v[52:53] op_sel_hi:[1,0]
	v_mul_f32_e32 v50, v1, v1
	v_mul_f32_e32 v51, v2, v2
	v_mov_b32_e32 v49, v46
	v_mov_b32_e32 v46, v45
	v_mov_b32_e32 v48, v44
	v_pk_mul_f32 v[42:43], v[46:47], v[42:43]
	v_pk_mul_f32 v[40:41], v[48:49], v[40:41]
	v_and_b32_sdwa v46, v43, v90 dst_sel:DWORD dst_unused:UNUSED_PAD src0_sel:WORD_1 src1_sel:DWORD
	v_and_b32_sdwa v47, v42, v90 dst_sel:DWORD dst_unused:UNUSED_PAD src0_sel:WORD_1 src1_sel:DWORD
	v_and_b32_sdwa v44, v41, v90 dst_sel:DWORD dst_unused:UNUSED_PAD src0_sel:WORD_1 src1_sel:DWORD
; __device__ __forceinline__ unsigned pk2(float lo, float hi) { return f2bf(lo) | (f2bf(hi) << 16); }
; __device__ __forceinline__ void p0_prologue(const Params& p, LAS unsigned char* lds, int G) {
;     ...
;         for (int q = 0; q < 4; ++q) { float a = 0.f;
; #pragma unroll
;             for (int j = 0; j < 4; ++j) a += (v[q][j][0] * v[q][j][0] + v[q][j][1] * v[q][j][1]) + (v[q][j][2] * v[q][j][2] + v[q][j][3] * v[q][j][3]);
;             s[q] = a; }
; #pragma unroll
;         for (int q = 0; q < 4; ++q) { const float rstd = __builtin_amdgcn_rsqf(wave_sum(s[q]) * (1.f / D) + EPS);
;             u32x2* o8 = (u32x2*)(XN + (size_t)(rb + q) * D) + lane;
; #pragma unroll
;             for (int j = 0; j < 4; ++j) { const f32x4 g = gp[64 * j]; u32x2 w; w.x = pk2(v[q][j][0] * rstd * g[0], v[q][j][1] * rstd * g[1]); w.y = pk2(v[q][j][2] * rstd * g[2], v[q][j][3] * rstd * g[3]); o8[64 * j] = w; } }
	v_and_b32_sdwa v45, v40, v90 dst_sel:DWORD dst_unused:UNUSED_PAD src0_sel:WORD_1 src1_sel:DWORD
	v_add3_u32 v43, v43, v46, s19
	v_add3_u32 v42, v42, v47, s19
	v_add3_u32 v40, v40, v45, s19
	v_add3_u32 v41, v41, v44, s19
	v_and_b32_e32 v43, 0xffff0000, v43
	v_and_b32_e32 v42, 0xffff0000, v42
	v_or_b32_sdwa v41, v43, v41 dst_sel:DWORD dst_unused:UNUSED_PAD src0_sel:DWORD src1_sel:WORD_1
	v_or_b32_sdwa v40, v42, v40 dst_sel:DWORD dst_unused:UNUSED_PAD src0_sel:DWORD src1_sel:WORD_1
	global_store_dwordx2 v[76:77], v[40:41], off offset:-3072
	v_mov_b32_e32 v40, v120
	v_mov_b32_e32 v41, v121
	v_mov_b32_e32 v42, v122
	v_mov_b32_e32 v43, v123
	v_mov_b32_e32 v44, v36
	v_mov_b32_e32 v45, v38
	v_mov_b32_e32 v38, v37
	v_pk_mul_f32 v[36:37], v[44:45], v[52:53] op_sel_hi:[1,0]
	v_pk_mul_f32 v[38:39], v[38:39], v[52:53] op_sel_hi:[1,0]
	v_mul_f32_e32 v47, v0, v0
	v_mul_f32_e32 v46, v7, v7
	v_mov_b32_e32 v45, v42
	v_mov_b32_e32 v42, v41
	v_mov_b32_e32 v44, v40
	v_pk_mul_f32 v[38:39], v[42:43], v[38:39]
	v_pk_mul_f32 v[36:37], v[44:45], v[36:37]
	v_and_b32_sdwa v42, v39, v90 dst_sel:DWORD dst_unused:UNUSED_PAD src0_sel:WORD_1 src1_sel:DWORD
	v_and_b32_sdwa v43, v38, v90 dst_sel:DWORD dst_unused:UNUSED_PAD src0_sel:WORD_1 src1_sel:DWORD
	v_and_b32_sdwa v40, v37, v90 dst_sel:DWORD dst_unused:UNUSED_PAD src0_sel:WORD_1 src1_sel:DWORD
	v_and_b32_sdwa v41, v36, v90 dst_sel:DWORD dst_unused:UNUSED_PAD src0_sel:WORD_1 src1_sel:DWORD
	v_add3_u32 v39, v39, v42, s19
	v_add3_u32 v38, v38, v43, s19
	v_add3_u32 v36, v36, v41, s19
	v_add3_u32 v37, v37, v40, s19
	v_and_b32_e32 v39, 0xffff0000, v39
	v_and_b32_e32 v38, 0xffff0000, v38
	v_or_b32_sdwa v37, v39, v37 dst_sel:DWORD dst_unused:UNUSED_PAD src0_sel:DWORD src1_sel:WORD_1
	v_or_b32_sdwa v36, v38, v36 dst_sel:DWORD dst_unused:UNUSED_PAD src0_sel:DWORD src1_sel:WORD_1
	global_store_dwordx2 v[76:77], v[36:37], off offset:-2560
	v_mov_b32_e32 v36, v124
	v_mov_b32_e32 v37, v125
	v_mov_b32_e32 v38, v126
	v_mov_b32_e32 v39, v127
	v_mov_b32_e32 v40, v28
	v_mov_b32_e32 v41, v30
	v_mov_b32_e32 v30, v29
	v_pk_mul_f32 v[28:29], v[40:41], v[52:53] op_sel_hi:[1,0]
	v_pk_mul_f32 v[30:31], v[30:31], v[52:53] op_sel_hi:[1,0]
	v_pk_mul_f32 v[42:43], v[8:9], v[8:9]
	v_mul_f32_e32 v44, v5, v5
	v_mul_f32_e32 v52, v3, v3
	v_mov_b32_e32 v41, v38
	v_mov_b32_e32 v38, v37
	v_mov_b32_e32 v40, v36
	v_pk_mul_f32 v[30:31], v[30:31], v[38:39]
	v_pk_mul_f32 v[28:29], v[28:29], v[40:41]
	v_and_b32_sdwa v38, v31, v90 dst_sel:DWORD dst_unused:UNUSED_PAD src0_sel:WORD_1 src1_sel:DWORD
	v_and_b32_sdwa v39, v30, v90 dst_sel:DWORD dst_unused:UNUSED_PAD src0_sel:WORD_1 src1_sel:DWORD
	v_and_b32_sdwa v36, v29, v90 dst_sel:DWORD dst_unused:UNUSED_PAD src0_sel:WORD_1 src1_sel:DWORD
	v_and_b32_sdwa v37, v28, v90 dst_sel:DWORD dst_unused:UNUSED_PAD src0_sel:WORD_1 src1_sel:DWORD
	v_add3_u32 v31, v31, v38, s19
	v_add3_u32 v30, v30, v39, s19
	v_add3_u32 v28, v28, v37, s19
	v_add3_u32 v29, v29, v36, s19
	v_and_b32_e32 v31, 0xffff0000, v31
	v_and_b32_e32 v30, 0xffff0000, v30
	v_or_b32_sdwa v29, v31, v29 dst_sel:DWORD dst_unused:UNUSED_PAD src0_sel:DWORD src1_sel:WORD_1
	v_or_b32_sdwa v28, v30, v28 dst_sel:DWORD dst_unused:UNUSED_PAD src0_sel:DWORD src1_sel:WORD_1
	global_store_dwordx2 v[76:77], v[28:29], off offset:-2048
	v_mov_b32_e32 v28, v112
	v_mov_b32_e32 v29, v113
	v_mov_b32_e32 v30, v114
	v_mov_b32_e32 v31, v115
	v_pk_mul_f32 v[36:37], v[18:19], v[18:19]
	v_pk_mul_f32 v[38:39], v[16:17], v[16:17]
	v_pk_mul_f32 v[40:41], v[10:11], v[10:11]
	v_pk_mov_b32 v[48:49], v[38:39], v[36:37] op_sel:[1,0]
	v_mov_b32_e32 v39, v37
	v_pk_mov_b32 v[36:37], v[42:43], v[40:41] op_sel:[1,0]
	v_mov_b32_e32 v43, v41
	v_pk_add_f32 v[38:39], v[48:49], v[38:39]
	v_pk_add_f32 v[36:37], v[36:37], v[42:43]
	v_pk_fma_f32 v[40:41], v[4:5], v[4:5], v[44:45] op_sel_hi:[1,1,0]
	v_pk_fma_f32 v[44:45], v[6:7], v[6:7], v[46:47] op_sel_hi:[1,1,0]
	v_pk_add_f32 v[38:39], v[38:39], v[38:39] op_sel:[0,1] op_sel_hi:[1,0]
	v_pk_add_f32 v[36:37], v[36:37], v[36:37] op_sel:[0,1] op_sel_hi:[1,0]
	v_mov_b32_e32 v41, v51
	v_mov_b32_e32 v45, v52
	v_mov_b32_e32 v39, v47
	v_mov_b32_e32 v37, v50
	v_pk_add_f32 v[40:41], v[40:41], v[44:45]
	v_pk_add_f32 v[36:37], v[38:39], v[36:37]
	v_mov_b32_e32 v38, v16
	v_pk_add_f32 v[36:37], v[36:37], v[40:41]
	v_mov_b32_e32 v39, v18
	v_add_f32_e32 v36, v36, v37
	ds_bpermute_b32 v37, v80, v36
	v_mov_b32_e32 v18, v17
	s_waitcnt lgkmcnt(0)
	v_add_f32_e32 v36, v36, v37
	ds_bpermute_b32 v37, v81, v36
	s_waitcnt lgkmcnt(0)
	v_add_f32_e32 v36, v36, v37
	ds_bpermute_b32 v37, v82, v36
	s_waitcnt lgkmcnt(0)
	v_add_f32_e32 v36, v36, v37
	ds_bpermute_b32 v37, v83, v36
	s_waitcnt lgkmcnt(0)
	v_add_f32_e32 v36, v36, v37
	ds_bpermute_b32 v37, v84, v36
	s_waitcnt lgkmcnt(0)
	v_add_f32_e32 v36, v36, v37
	ds_bpermute_b32 v37, v85, v36
	s_waitcnt lgkmcnt(0)
; __device__ __forceinline__ unsigned pk2(float lo, float hi) { return f2bf(lo) | (f2bf(hi) << 16); }
; __device__ __forceinline__ void p0_prologue(const Params& p, LAS unsigned char* lds, int G) {
;     ...
;         for (int q = 0; q < 4; ++q) { float a = 0.f;
; #pragma unroll
;             for (int j = 0; j < 4; ++j) a += (v[q][j][0] * v[q][j][0] + v[q][j][1] * v[q][j][1]) + (v[q][j][2] * v[q][j][2] + v[q][j][3] * v[q][j][3]);
;             s[q] = a; }
; #pragma unroll
;         for (int q = 0; q < 4; ++q) { const float rstd = __builtin_amdgcn_rsqf(wave_sum(s[q]) * (1.f / D) + EPS);
;             u32x2* o8 = (u32x2*)(XN + (size_t)(rb + q) * D) + lane;
; #pragma unroll
;             for (int j = 0; j < 4; ++j) { const f32x4 g = gp[64 * j]; u32x2 w; w.x = pk2(v[q][j][0] * rstd * g[0], v[q][j][1] * rstd * g[1]); w.y = pk2(v[q][j][2] * rstd * g[2], v[q][j][3] * rstd * g[3]); o8[64 * j] = w; } }
	v_add_f32_e32 v36, v36, v37
	v_fmamk_f32 v36, v36, 0x3a800000, v89
	v_rsq_f32_e32 v36, v36
	s_nop 0
	v_pk_mul_f32 v[16:17], v[38:39], v[36:37] op_sel_hi:[1,0]
	v_pk_mul_f32 v[18:19], v[18:19], v[36:37] op_sel_hi:[1,0]
	v_mov_b32_e32 v39, v30
	v_mov_b32_e32 v30, v29
	v_mov_b32_e32 v38, v28
	v_pk_mul_f32 v[18:19], v[30:31], v[18:19]
	v_pk_mul_f32 v[16:17], v[38:39], v[16:17]
	v_and_b32_sdwa v30, v19, v90 dst_sel:DWORD dst_unused:UNUSED_PAD src0_sel:WORD_1 src1_sel:DWORD
	v_and_b32_sdwa v31, v18, v90 dst_sel:DWORD dst_unused:UNUSED_PAD src0_sel:WORD_1 src1_sel:DWORD
	v_and_b32_sdwa v28, v17, v90 dst_sel:DWORD dst_unused:UNUSED_PAD src0_sel:WORD_1 src1_sel:DWORD
	v_and_b32_sdwa v29, v16, v90 dst_sel:DWORD dst_unused:UNUSED_PAD src0_sel:WORD_1 src1_sel:DWORD
	v_add3_u32 v19, v19, v30, s19
	v_add3_u32 v18, v18, v31, s19
	v_add3_u32 v16, v16, v29, s19
	v_add3_u32 v17, v17, v28, s19
	v_and_b32_e32 v19, 0xffff0000, v19
	v_and_b32_e32 v18, 0xffff0000, v18
	v_or_b32_sdwa v17, v19, v17 dst_sel:DWORD dst_unused:UNUSED_PAD src0_sel:DWORD src1_sel:WORD_1
	v_or_b32_sdwa v16, v18, v16 dst_sel:DWORD dst_unused:UNUSED_PAD src0_sel:DWORD src1_sel:WORD_1
	global_store_dwordx2 v[76:77], v[16:17], off offset:-1536
	v_mov_b32_e32 v16, v116
	v_mov_b32_e32 v17, v117
	v_mov_b32_e32 v18, v118
	v_mov_b32_e32 v19, v119
	v_mov_b32_e32 v28, v8
	v_mov_b32_e32 v29, v10
	v_mov_b32_e32 v10, v9
	v_pk_mul_f32 v[8:9], v[28:29], v[36:37] op_sel_hi:[1,0]
	v_pk_mul_f32 v[10:11], v[10:11], v[36:37] op_sel_hi:[1,0]
	v_mul_f32_e32 v30, v13, v13
	v_mul_f32_e32 v31, v14, v14
	v_mov_b32_e32 v29, v18
	v_mov_b32_e32 v18, v17
	v_mov_b32_e32 v28, v16
	v_pk_mul_f32 v[10:11], v[18:19], v[10:11]
	v_pk_mul_f32 v[8:9], v[28:29], v[8:9]
	v_and_b32_sdwa v18, v11, v90 dst_sel:DWORD dst_unused:UNUSED_PAD src0_sel:WORD_1 src1_sel:DWORD
	v_and_b32_sdwa v19, v10, v90 dst_sel:DWORD dst_unused:UNUSED_PAD src0_sel:WORD_1 src1_sel:DWORD
	v_and_b32_sdwa v16, v9, v90 dst_sel:DWORD dst_unused:UNUSED_PAD src0_sel:WORD_1 src1_sel:DWORD
	v_and_b32_sdwa v17, v8, v90 dst_sel:DWORD dst_unused:UNUSED_PAD src0_sel:WORD_1 src1_sel:DWORD
	v_add3_u32 v11, v11, v18, s19
	v_add3_u32 v10, v10, v19, s19
	v_add3_u32 v8, v8, v17, s19
	v_add3_u32 v9, v9, v16, s19
	v_and_b32_e32 v11, 0xffff0000, v11
	v_and_b32_e32 v10, 0xffff0000, v10
	v_or_b32_sdwa v9, v11, v9 dst_sel:DWORD dst_unused:UNUSED_PAD src0_sel:DWORD src1_sel:WORD_1
	v_or_b32_sdwa v8, v10, v8 dst_sel:DWORD dst_unused:UNUSED_PAD src0_sel:DWORD src1_sel:WORD_1
	global_store_dwordx2 v[76:77], v[8:9], off offset:-1024
	v_mov_b32_e32 v8, v120
	v_mov_b32_e32 v9, v121
	v_mov_b32_e32 v10, v122
	v_mov_b32_e32 v11, v123
	v_mov_b32_e32 v16, v4
	v_mov_b32_e32 v17, v6
	v_mov_b32_e32 v6, v5
	v_pk_mul_f32 v[4:5], v[16:17], v[36:37] op_sel_hi:[1,0]
	v_pk_mul_f32 v[6:7], v[6:7], v[36:37] op_sel_hi:[1,0]
	v_mul_f32_e32 v19, v12, v12
	v_mul_f32_e32 v18, v23, v23
	v_mov_b32_e32 v17, v10
	v_mov_b32_e32 v10, v9
	v_mov_b32_e32 v16, v8
	v_pk_mul_f32 v[6:7], v[10:11], v[6:7]
	v_pk_mul_f32 v[4:5], v[16:17], v[4:5]
	v_and_b32_sdwa v10, v7, v90 dst_sel:DWORD dst_unused:UNUSED_PAD src0_sel:WORD_1 src1_sel:DWORD
	v_and_b32_sdwa v11, v6, v90 dst_sel:DWORD dst_unused:UNUSED_PAD src0_sel:WORD_1 src1_sel:DWORD
	v_and_b32_sdwa v8, v5, v90 dst_sel:DWORD dst_unused:UNUSED_PAD src0_sel:WORD_1 src1_sel:DWORD
	v_and_b32_sdwa v9, v4, v90 dst_sel:DWORD dst_unused:UNUSED_PAD src0_sel:WORD_1 src1_sel:DWORD
	v_add3_u32 v7, v7, v10, s19
	v_add3_u32 v6, v6, v11, s19
	v_add3_u32 v4, v4, v9, s19
	v_add3_u32 v5, v5, v8, s19
	v_and_b32_e32 v7, 0xffff0000, v7
	v_and_b32_e32 v6, 0xffff0000, v6
	v_or_b32_sdwa v5, v7, v5 dst_sel:DWORD dst_unused:UNUSED_PAD src0_sel:DWORD src1_sel:WORD_1
	v_or_b32_sdwa v4, v6, v4 dst_sel:DWORD dst_unused:UNUSED_PAD src0_sel:DWORD src1_sel:WORD_1
	global_store_dwordx2 v[76:77], v[4:5], off offset:-512
	v_mov_b32_e32 v4, v124
	v_mov_b32_e32 v5, v125
	v_mov_b32_e32 v6, v126
	v_mov_b32_e32 v7, v127
	v_mov_b32_e32 v8, v0
	v_mov_b32_e32 v9, v2
	v_mov_b32_e32 v2, v1
	v_pk_mul_f32 v[0:1], v[8:9], v[36:37] op_sel_hi:[1,0]
	v_pk_mul_f32 v[2:3], v[2:3], v[36:37] op_sel_hi:[1,0]
	v_pk_mul_f32 v[10:11], v[24:25], v[24:25]
	v_mul_f32_e32 v16, v21, v21
	v_mul_f32_e32 v36, v15, v15
	v_mov_b32_e32 v9, v6
	v_mov_b32_e32 v6, v5
	v_mov_b32_e32 v8, v4
	v_pk_mul_f32 v[2:3], v[2:3], v[6:7]
	v_pk_mul_f32 v[0:1], v[0:1], v[8:9]
	v_and_b32_sdwa v6, v3, v90 dst_sel:DWORD dst_unused:UNUSED_PAD src0_sel:WORD_1 src1_sel:DWORD
	v_and_b32_sdwa v7, v2, v90 dst_sel:DWORD dst_unused:UNUSED_PAD src0_sel:WORD_1 src1_sel:DWORD
	v_and_b32_sdwa v4, v1, v90 dst_sel:DWORD dst_unused:UNUSED_PAD src0_sel:WORD_1 src1_sel:DWORD
	v_and_b32_sdwa v5, v0, v90 dst_sel:DWORD dst_unused:UNUSED_PAD src0_sel:WORD_1 src1_sel:DWORD
	v_add3_u32 v3, v3, v6, s19
	v_add3_u32 v2, v2, v7, s19
	v_add3_u32 v0, v0, v5, s19
	v_add3_u32 v1, v1, v4, s19
	v_and_b32_e32 v3, 0xffff0000, v3
	v_and_b32_e32 v2, 0xffff0000, v2
	v_or_b32_sdwa v1, v3, v1 dst_sel:DWORD dst_unused:UNUSED_PAD src0_sel:DWORD src1_sel:WORD_1
	v_or_b32_sdwa v0, v2, v0 dst_sel:DWORD dst_unused:UNUSED_PAD src0_sel:DWORD src1_sel:WORD_1
	global_store_dwordx2 v[76:77], v[0:1], off
	v_mov_b32_e32 v0, v112
	v_mov_b32_e32 v1, v113
	v_mov_b32_e32 v2, v114
	v_mov_b32_e32 v3, v115
	v_pk_mul_f32 v[4:5], v[34:35], v[34:35]
	v_pk_mul_f32 v[6:7], v[32:33], v[32:33]
	v_pk_mul_f32 v[8:9], v[26:27], v[26:27]
	v_pk_mov_b32 v[28:29], v[6:7], v[4:5] op_sel:[1,0]
	v_mov_b32_e32 v7, v5
	v_pk_mov_b32 v[4:5], v[10:11], v[8:9] op_sel:[1,0]
	v_mov_b32_e32 v11, v9
	v_pk_add_f32 v[6:7], v[28:29], v[6:7]
	v_pk_add_f32 v[4:5], v[4:5], v[10:11]
	v_pk_fma_f32 v[8:9], v[20:21], v[20:21], v[16:17] op_sel_hi:[1,1,0]
	v_pk_fma_f32 v[16:17], v[22:23], v[22:23], v[18:19] op_sel_hi:[1,1,0]
	v_pk_add_f32 v[6:7], v[6:7], v[6:7] op_sel:[0,1] op_sel_hi:[1,0]
	v_pk_add_f32 v[4:5], v[4:5], v[4:5] op_sel:[0,1] op_sel_hi:[1,0]
	v_mov_b32_e32 v9, v31
	v_mov_b32_e32 v17, v36
	v_mov_b32_e32 v7, v19
	v_mov_b32_e32 v5, v30
	v_pk_add_f32 v[8:9], v[8:9], v[16:17]
	v_pk_add_f32 v[4:5], v[6:7], v[4:5]
	v_lshl_add_u64 v[76:77], v[76:77], 0, s[10:11]
	v_pk_add_f32 v[4:5], v[4:5], v[8:9]
	v_mov_b32_e32 v9, v34
	v_add_f32_e32 v4, v4, v5
	ds_bpermute_b32 v5, v80, v4
	v_mov_b32_e32 v34, v33
	v_mov_b32_e32 v8, v32
	s_waitcnt lgkmcnt(0)
; __device__ __forceinline__ unsigned pk2(float lo, float hi) { return f2bf(lo) | (f2bf(hi) << 16); }
; __device__ __forceinline__ void p0_prologue(const Params& p, LAS unsigned char* lds, int G) {
;     ...
;         for (int q = 0; q < 4; ++q) { float a = 0.f;
; #pragma unroll
;             for (int j = 0; j < 4; ++j) a += (v[q][j][0] * v[q][j][0] + v[q][j][1] * v[q][j][1]) + (v[q][j][2] * v[q][j][2] + v[q][j][3] * v[q][j][3]);
;             s[q] = a; }
; #pragma unroll
;         for (int q = 0; q < 4; ++q) { const float rstd = __builtin_amdgcn_rsqf(wave_sum(s[q]) * (1.f / D) + EPS);
;             u32x2* o8 = (u32x2*)(XN + (size_t)(rb + q) * D) + lane;
; #pragma unroll
;             for (int j = 0; j < 4; ++j) { const f32x4 g = gp[64 * j]; u32x2 w; w.x = pk2(v[q][j][0] * rstd * g[0], v[q][j][1] * rstd * g[1]); w.y = pk2(v[q][j][2] * rstd * g[2], v[q][j][3] * rstd * g[3]); o8[64 * j] = w; } }
	v_add_f32_e32 v4, v4, v5
	ds_bpermute_b32 v5, v81, v4
	s_waitcnt lgkmcnt(0)
	v_add_f32_e32 v4, v4, v5
	ds_bpermute_b32 v5, v82, v4
	s_waitcnt lgkmcnt(0)
	v_add_f32_e32 v4, v4, v5
	ds_bpermute_b32 v5, v83, v4
	s_waitcnt lgkmcnt(0)
	v_add_f32_e32 v4, v4, v5
	ds_bpermute_b32 v5, v84, v4
	s_waitcnt lgkmcnt(0)
	v_add_f32_e32 v6, v4, v5
	ds_bpermute_b32 v7, v85, v6
	v_lshlrev_b64 v[4:5], 11, v[78:79]
	v_lshl_add_u64 v[4:5], v[70:71], 0, v[4:5]
	s_waitcnt lgkmcnt(0)
	v_add_f32_e32 v6, v6, v7
	v_fmamk_f32 v6, v6, 0x3a800000, v89
	v_rsq_f32_e32 v6, v6
	v_mov_b32_e32 v17, v2
	v_pk_mul_f32 v[10:11], v[34:35], v[6:7] op_sel_hi:[1,0]
	v_mov_b32_e32 v2, v1
	v_pk_mul_f32 v[8:9], v[8:9], v[6:7] op_sel_hi:[1,0]
	v_mov_b32_e32 v16, v0
	v_pk_mul_f32 v[2:3], v[2:3], v[10:11]
	v_pk_mul_f32 v[0:1], v[16:17], v[8:9]
	v_and_b32_sdwa v9, v3, v90 dst_sel:DWORD dst_unused:UNUSED_PAD src0_sel:WORD_1 src1_sel:DWORD
	v_and_b32_sdwa v10, v2, v90 dst_sel:DWORD dst_unused:UNUSED_PAD src0_sel:WORD_1 src1_sel:DWORD
	v_and_b32_sdwa v7, v1, v90 dst_sel:DWORD dst_unused:UNUSED_PAD src0_sel:WORD_1 src1_sel:DWORD
	v_and_b32_sdwa v8, v0, v90 dst_sel:DWORD dst_unused:UNUSED_PAD src0_sel:WORD_1 src1_sel:DWORD
	v_add3_u32 v3, v3, v9, s19
	v_add3_u32 v2, v2, v10, s19
	v_add3_u32 v0, v0, v8, s19
	v_add3_u32 v1, v1, v7, s19
	v_and_b32_e32 v3, 0xffff0000, v3
	v_and_b32_e32 v2, 0xffff0000, v2
	v_or_b32_sdwa v1, v3, v1 dst_sel:DWORD dst_unused:UNUSED_PAD src0_sel:DWORD src1_sel:WORD_1
	v_or_b32_sdwa v0, v2, v0 dst_sel:DWORD dst_unused:UNUSED_PAD src0_sel:DWORD src1_sel:WORD_1
	global_store_dwordx2 v[4:5], v[0:1], off
	v_mov_b32_e32 v0, v116
	v_mov_b32_e32 v1, v117
	v_mov_b32_e32 v2, v118
	v_mov_b32_e32 v3, v119
	v_mov_b32_e32 v9, v26
	v_mov_b32_e32 v26, v25
	v_mov_b32_e32 v8, v24
	v_pk_mul_f32 v[10:11], v[26:27], v[6:7] op_sel_hi:[1,0]
	v_pk_mul_f32 v[8:9], v[8:9], v[6:7] op_sel_hi:[1,0]
	v_mov_b32_e32 v17, v2
	v_mov_b32_e32 v2, v1
	v_mov_b32_e32 v16, v0
	v_pk_mul_f32 v[2:3], v[2:3], v[10:11]
	v_pk_mul_f32 v[0:1], v[16:17], v[8:9]
	v_and_b32_sdwa v9, v3, v90 dst_sel:DWORD dst_unused:UNUSED_PAD src0_sel:WORD_1 src1_sel:DWORD
	v_and_b32_sdwa v10, v2, v90 dst_sel:DWORD dst_unused:UNUSED_PAD src0_sel:WORD_1 src1_sel:DWORD
	v_and_b32_sdwa v7, v1, v90 dst_sel:DWORD dst_unused:UNUSED_PAD src0_sel:WORD_1 src1_sel:DWORD
	v_and_b32_sdwa v8, v0, v90 dst_sel:DWORD dst_unused:UNUSED_PAD src0_sel:WORD_1 src1_sel:DWORD
	v_add3_u32 v3, v3, v9, s19
	v_add3_u32 v2, v2, v10, s19
	v_add3_u32 v0, v0, v8, s19
	v_add3_u32 v1, v1, v7, s19
	v_and_b32_e32 v3, 0xffff0000, v3
	v_and_b32_e32 v2, 0xffff0000, v2
	v_or_b32_sdwa v1, v3, v1 dst_sel:DWORD dst_unused:UNUSED_PAD src0_sel:DWORD src1_sel:WORD_1
	v_or_b32_sdwa v0, v2, v0 dst_sel:DWORD dst_unused:UNUSED_PAD src0_sel:DWORD src1_sel:WORD_1
	global_store_dwordx2 v[4:5], v[0:1], off offset:512
	v_mov_b32_e32 v0, v120
	v_mov_b32_e32 v1, v121
	v_mov_b32_e32 v2, v122
	v_mov_b32_e32 v3, v123
	v_mov_b32_e32 v9, v22
	v_mov_b32_e32 v22, v21
	v_mov_b32_e32 v8, v20
	v_pk_mul_f32 v[10:11], v[22:23], v[6:7] op_sel_hi:[1,0]
	v_pk_mul_f32 v[8:9], v[8:9], v[6:7] op_sel_hi:[1,0]
	v_mov_b32_e32 v17, v2
	v_mov_b32_e32 v2, v1
	v_mov_b32_e32 v16, v0
	v_pk_mul_f32 v[2:3], v[2:3], v[10:11]
	v_pk_mul_f32 v[0:1], v[16:17], v[8:9]
	v_and_b32_sdwa v9, v3, v90 dst_sel:DWORD dst_unused:UNUSED_PAD src0_sel:WORD_1 src1_sel:DWORD
	v_and_b32_sdwa v10, v2, v90 dst_sel:DWORD dst_unused:UNUSED_PAD src0_sel:WORD_1 src1_sel:DWORD
	v_and_b32_sdwa v7, v1, v90 dst_sel:DWORD dst_unused:UNUSED_PAD src0_sel:WORD_1 src1_sel:DWORD
	v_and_b32_sdwa v8, v0, v90 dst_sel:DWORD dst_unused:UNUSED_PAD src0_sel:WORD_1 src1_sel:DWORD
	v_add3_u32 v3, v3, v9, s19
	v_add3_u32 v2, v2, v10, s19
	v_add3_u32 v0, v0, v8, s19
	v_add3_u32 v1, v1, v7, s19
	v_and_b32_e32 v3, 0xffff0000, v3
	v_and_b32_e32 v2, 0xffff0000, v2
	v_or_b32_sdwa v1, v3, v1 dst_sel:DWORD dst_unused:UNUSED_PAD src0_sel:DWORD src1_sel:WORD_1
	v_or_b32_sdwa v0, v2, v0 dst_sel:DWORD dst_unused:UNUSED_PAD src0_sel:DWORD src1_sel:WORD_1
	global_store_dwordx2 v[4:5], v[0:1], off offset:1024
	v_mov_b32_e32 v0, v124
	v_mov_b32_e32 v1, v125
	v_mov_b32_e32 v2, v126
	v_mov_b32_e32 v3, v127
	v_mov_b32_e32 v8, v12
	v_mov_b32_e32 v9, v14
	v_mov_b32_e32 v14, v13
	v_pk_mul_f32 v[8:9], v[8:9], v[6:7] op_sel_hi:[1,0]
	v_pk_mul_f32 v[6:7], v[14:15], v[6:7] op_sel_hi:[1,0]
	v_mov_b32_e32 v11, v2
	v_mov_b32_e32 v2, v1
	v_mov_b32_e32 v10, v0
	v_pk_mul_f32 v[2:3], v[6:7], v[2:3]
	v_pk_mul_f32 v[0:1], v[8:9], v[10:11]
	v_and_b32_sdwa v8, v3, v90 dst_sel:DWORD dst_unused:UNUSED_PAD src0_sel:WORD_1 src1_sel:DWORD
	v_and_b32_sdwa v9, v2, v90 dst_sel:DWORD dst_unused:UNUSED_PAD src0_sel:WORD_1 src1_sel:DWORD
	v_and_b32_sdwa v6, v1, v90 dst_sel:DWORD dst_unused:UNUSED_PAD src0_sel:WORD_1 src1_sel:DWORD
	v_and_b32_sdwa v7, v0, v90 dst_sel:DWORD dst_unused:UNUSED_PAD src0_sel:WORD_1 src1_sel:DWORD
	v_add3_u32 v3, v3, v8, s19
	v_add3_u32 v2, v2, v9, s19
	v_add3_u32 v0, v0, v7, s19
	v_add3_u32 v1, v1, v6, s19
	v_and_b32_e32 v3, 0xffff0000, v3
	v_and_b32_e32 v2, 0xffff0000, v2
	v_or_b32_sdwa v1, v3, v1 dst_sel:DWORD dst_unused:UNUSED_PAD src0_sel:DWORD src1_sel:WORD_1
	v_or_b32_sdwa v0, v2, v0 dst_sel:DWORD dst_unused:UNUSED_PAD src0_sel:DWORD src1_sel:WORD_1
	global_store_dwordx2 v[4:5], v[0:1], off offset:1536
	s_andn2_b64 exec, exec, s[16:17]
	s_cbranch_execz .LBB0_174
; __device__ __forceinline__ void p0_prologue(const Params& p, LAS unsigned char* lds, int G) {
;     ...
;     for (int rb = gw * 4; rb < T; rb += NGW * 4) {
;         f32x4 v[4][4]; float s[4];
; #pragma unroll
;         for (int q = 0; q < 4; ++q) { const int row = rb + q; const float* xrow = row < TP ? p.in[0] + (size_t)row * D : p.in[1] + (size_t)(row - TP) * D; const f32x4* xr = (const f32x4*)xrow + lane;
; #pragma unroll
;             for (int j = 0; j < 4; ++j) v[q][j] = xr[64 * j]; }
.LBB0_172:
	v_add_u32_e32 v2, 0xffff7fff, v72
	v_lshl_add_u64 v[0:1], v[72:73], 0, -1
	v_cmp_gt_i32_e32 vcc, s18, v66
	v_lshl_add_u64 v[78:79], v[72:73], 0, 2
	s_nop 0
	v_cndmask_b32_e32 v1, 0, v1, vcc
	v_cndmask_b32_e32 v0, v2, v0, vcc
	v_cndmask_b32_e32 v3, v67, v86, vcc
	v_cndmask_b32_e32 v2, v87, v88, vcc
	v_lshlrev_b64 v[0:1], 12, v[0:1]
	v_lshl_add_u64 v[0:1], v[2:3], 0, v[0:1]
	v_lshl_add_u64 v[0:1], v[0:1], 0, v[64:65]
	global_load_dwordx4 v[60:63], v[0:1], off nt
	global_load_dwordx4 v[56:59], v[0:1], off offset:1024 nt
	global_load_dwordx4 v[52:55], v[0:1], off offset:2048 nt
	global_load_dwordx4 v[48:51], v[0:1], off offset:3072 nt
	v_add_u32_e32 v0, 0xffff8000, v72
	v_cmp_gt_i32_e32 vcc, s18, v72
	s_nop 1
	v_cndmask_b32_e32 v1, 0, v73, vcc
	v_cndmask_b32_e32 v0, v0, v72, vcc
	v_cndmask_b32_e32 v3, v67, v86, vcc
	v_cndmask_b32_e32 v2, v87, v88, vcc
	v_lshlrev_b64 v[0:1], 12, v[0:1]
	v_lshl_add_u64 v[0:1], v[2:3], 0, v[0:1]
	v_lshl_add_u64 v[0:1], v[0:1], 0, v[64:65]
	global_load_dwordx4 v[44:47], v[0:1], off nt
	global_load_dwordx4 v[40:43], v[0:1], off offset:1024 nt
	global_load_dwordx4 v[36:39], v[0:1], off offset:2048 nt
	global_load_dwordx4 v[28:31], v[0:1], off offset:3072 nt
	v_lshl_add_u64 v[0:1], v[72:73], 0, 1
	v_add_u32_e32 v2, 0xffff8001, v72
	v_cmp_gt_i32_e32 vcc, s18, v0
	s_nop 1
	v_cndmask_b32_e32 v1, 0, v1, vcc
	v_cndmask_b32_e32 v0, v2, v0, vcc
	v_cndmask_b32_e32 v3, v67, v86, vcc
	v_cndmask_b32_e32 v2, v87, v88, vcc
	v_lshlrev_b64 v[0:1], 12, v[0:1]
	v_lshl_add_u64 v[0:1], v[2:3], 0, v[0:1]
	v_lshl_add_u64 v[12:13], v[0:1], 0, v[64:65]
	global_load_dwordx4 v[16:19], v[12:13], off nt
	global_load_dwordx4 v[8:11], v[12:13], off offset:1024 nt
	global_load_dwordx4 v[4:7], v[12:13], off offset:2048 nt
	global_load_dwordx4 v[0:3], v[12:13], off offset:3072 nt
	v_cmp_lt_i32_e32 vcc, s19, v78
	v_mov_b64_e32 v[12:13], v[74:75]
	s_and_saveexec_b64 s[0:1], vcc
	s_cbranch_execz .LBB0_171
	v_add_u32_e32 v12, 0xffff8002, v72
	v_mov_b32_e32 v13, v65
	v_lshlrev_b64 v[12:13], 12, v[12:13]
	v_lshl_add_u64 v[12:13], s[2:3], 0, v[12:13]
	v_mov_b32_e32 v79, v65
	s_branch .LBB0_171
